# K-loop: 3/5 DMA split variant of the trimmed no-setprio loop
# baseline (speedup 1.0000x reference)
.LBB0_176:
	v_add_u32_e32 v130, 0x10000, v243
	v_add_u32_e32 v142, 0x14000, v243
	ds_read_b128 v[146:149], v130
	ds_read_b128 v[150:153], v130 offset:1024
	ds_read_b128 v[154:157], v130 offset:2048
	ds_read_b128 v[158:161], v130 offset:3072
	ds_read_b128 v[130:133], v142
	ds_read_b128 v[134:137], v142 offset:1024
	ds_read_b128 v[138:141], v142 offset:2048
	ds_read_b128 v[142:145], v142 offset:3072
	v_lshl_add_u64 v[246:247], v[234:235], 0, s[80:81]
	s_add_i32 m0, s8, 0xc000
	s_waitcnt lgkmcnt(0)
	ds_read_b128 v[174:177], v244
	ds_read_b128 v[190:193], v244 offset:1024
	ds_read_b128 v[170:173], v244 offset:2048
	ds_read_b128 v[186:189], v244 offset:3072
	ds_read_b128 v[166:169], v244 offset:4096
	ds_read_b128 v[182:185], v244 offset:5120
	ds_read_b128 v[162:165], v244 offset:6144
	ds_read_b128 v[178:181], v244 offset:7168
	s_mov_b32 m0, s67
	s_nop 0
	global_load_lds_dwordx4 v196, s[100:101]
	s_add_i32 m0, s8, 0xc000
	s_nop 0
	global_load_lds_dwordx4 v[246:247], off
	v_lshl_add_u64 v[246:247], v[236:237], 0, s[80:81]
	s_add_i32 m0, s8, 0xe000
	s_nop 0
	global_load_lds_dwordx4 v[246:247], off
	s_waitcnt vmcnt(8) lgkmcnt(0)
	s_barrier
	v_mfma_f32_16x16x32_bf16 v[118:121], v[146:149], v[174:177], v[118:121]
	v_mfma_f32_16x16x32_bf16 v[126:129], v[154:157], v[174:177], v[126:129]
	v_mfma_f32_16x16x32_bf16 v[102:105], v[146:149], v[170:173], v[102:105]
	v_mfma_f32_16x16x32_bf16 v[110:113], v[154:157], v[170:173], v[110:113]
	v_mfma_f32_16x16x32_bf16 v[86:89], v[146:149], v[166:169], v[86:89]
	v_mfma_f32_16x16x32_bf16 v[94:97], v[154:157], v[166:169], v[94:97]
	v_mfma_f32_16x16x32_bf16 v[70:73], v[146:149], v[162:165], v[70:73]
	v_mfma_f32_16x16x32_bf16 v[78:81], v[154:157], v[162:165], v[78:81]
	v_mfma_f32_16x16x32_bf16 v[118:121], v[150:153], v[190:193], v[118:121]
	v_mfma_f32_16x16x32_bf16 v[126:129], v[158:161], v[190:193], v[126:129]
	v_mfma_f32_16x16x32_bf16 v[102:105], v[150:153], v[186:189], v[102:105]
	v_mfma_f32_16x16x32_bf16 v[110:113], v[158:161], v[186:189], v[110:113]
	v_mfma_f32_16x16x32_bf16 v[86:89], v[150:153], v[182:185], v[86:89]
	v_mfma_f32_16x16x32_bf16 v[94:97], v[158:161], v[182:185], v[94:97]
	v_mfma_f32_16x16x32_bf16 v[70:73], v[150:153], v[178:181], v[70:73]
	v_mfma_f32_16x16x32_bf16 v[78:81], v[158:161], v[178:181], v[78:81]
	v_mfma_f32_16x16x32_bf16 v[122:125], v[130:133], v[174:177], v[122:125]
	v_mfma_f32_16x16x32_bf16 v[114:117], v[138:141], v[174:177], v[114:117]
	v_mfma_f32_16x16x32_bf16 v[106:109], v[130:133], v[170:173], v[106:109]
	v_mfma_f32_16x16x32_bf16 v[98:101], v[138:141], v[170:173], v[98:101]
	v_mfma_f32_16x16x32_bf16 v[90:93], v[130:133], v[166:169], v[90:93]
	v_mfma_f32_16x16x32_bf16 v[82:85], v[138:141], v[166:169], v[82:85]
	v_mfma_f32_16x16x32_bf16 v[74:77], v[130:133], v[162:165], v[74:77]
	v_mfma_f32_16x16x32_bf16 v[66:69], v[138:141], v[162:165], v[66:69]
	v_mfma_f32_16x16x32_bf16 v[122:125], v[134:137], v[190:193], v[122:125]
	v_mfma_f32_16x16x32_bf16 v[114:117], v[142:145], v[190:193], v[114:117]
	v_mfma_f32_16x16x32_bf16 v[106:109], v[134:137], v[186:189], v[106:109]
	v_mfma_f32_16x16x32_bf16 v[98:101], v[142:145], v[186:189], v[98:101]
	v_mfma_f32_16x16x32_bf16 v[90:93], v[134:137], v[182:185], v[90:93]
	v_mfma_f32_16x16x32_bf16 v[82:85], v[142:145], v[182:185], v[82:85]
	v_mfma_f32_16x16x32_bf16 v[74:77], v[134:137], v[178:181], v[74:77]
	v_mfma_f32_16x16x32_bf16 v[66:69], v[142:145], v[178:181], v[66:69]
	s_barrier
	s_andn2_b64 s[48:49], exec, s[50:51]
	s_andn2_b64 vcc, exec, s[50:51]
	s_cbranch_vccnz .LBB0_178
	ds_read_b128 v[174:177], v244 offset:16384
	ds_read_b128 v[190:193], v244 offset:17408
	ds_read_b128 v[170:173], v244 offset:18432
	ds_read_b128 v[186:189], v244 offset:19456
	ds_read_b128 v[166:169], v244 offset:20480
	ds_read_b128 v[182:185], v244 offset:21504
	ds_read_b128 v[162:165], v244 offset:22528
	ds_read_b128 v[178:181], v244 offset:23552
.LBB0_178:
	s_add_u32 s82, s0, s80
	s_addc_u32 s83, s1, s81
	s_add_u32 s84, s82, 0x460000
	s_addc_u32 s85, s83, 0
	s_cmp_eq_u32 s80, 0x41a0000
	s_cselect_b64 s[86:87], -1, 0
	s_and_b64 s[82:83], s[86:87], exec
	s_cselect_b32 s83, s71, s97
	s_cselect_b32 s82, s73, s79
	s_mov_b32 m0, s9
	s_cselect_b32 s85, s22, s85
	s_cselect_b32 s84, s69, s84
	s_add_u32 vcc_lo, s82, 0x4000
	global_load_lds_dwordx4 v194, s[82:83]
	s_mov_b32 m0, s10
	s_addc_u32 vcc_hi, s83, 0
	global_load_lds_dwordx4 v196, s[82:83]
	s_mov_b32 m0, s11
	s_nop 0
	global_load_lds_dwordx4 v194, vcc
	v_lshl_add_u64 v[246:247], vcc, 0, v[196:197]
	s_mov_b32 m0, s12
	s_and_b64 vcc, exec, s[48:49]
	global_load_lds_dwordx4 v[246:247], off
	s_mov_b32 m0, s8
	s_nop 0
	global_load_lds_dwordx4 v194, s[84:85]
	s_mov_b64 s[98:99], s[84:85]
	s_waitcnt vmcnt(7) lgkmcnt(0)
	s_barrier
	s_cbranch_vccnz .LBB0_180
	s_waitcnt lgkmcnt(0)
	v_mfma_f32_16x16x32_bf16 v[54:57], v[146:149], v[174:177], v[54:57]
	v_mfma_f32_16x16x32_bf16 v[62:65], v[154:157], v[174:177], v[62:65]
	v_mfma_f32_16x16x32_bf16 v[38:41], v[146:149], v[170:173], v[38:41]
	v_mfma_f32_16x16x32_bf16 v[46:49], v[154:157], v[170:173], v[46:49]
	v_mfma_f32_16x16x32_bf16 v[22:25], v[146:149], v[166:169], v[22:25]
	v_mfma_f32_16x16x32_bf16 v[30:33], v[154:157], v[166:169], v[30:33]
	v_mfma_f32_16x16x32_bf16 v[10:13], v[146:149], v[162:165], v[10:13]
	v_mfma_f32_16x16x32_bf16 v[14:17], v[154:157], v[162:165], v[14:17]
	v_mfma_f32_16x16x32_bf16 v[54:57], v[150:153], v[190:193], v[54:57]
	v_mfma_f32_16x16x32_bf16 v[62:65], v[158:161], v[190:193], v[62:65]
	v_mfma_f32_16x16x32_bf16 v[38:41], v[150:153], v[186:189], v[38:41]
	v_mfma_f32_16x16x32_bf16 v[46:49], v[158:161], v[186:189], v[46:49]
	v_mfma_f32_16x16x32_bf16 v[22:25], v[150:153], v[182:185], v[22:25]
	v_mfma_f32_16x16x32_bf16 v[30:33], v[158:161], v[182:185], v[30:33]
	v_mfma_f32_16x16x32_bf16 v[10:13], v[150:153], v[178:181], v[10:13]
	v_mfma_f32_16x16x32_bf16 v[14:17], v[158:161], v[178:181], v[14:17]
	v_mfma_f32_16x16x32_bf16 v[58:61], v[130:133], v[174:177], v[58:61]
	v_mfma_f32_16x16x32_bf16 v[50:53], v[138:141], v[174:177], v[50:53]
	v_mfma_f32_16x16x32_bf16 v[42:45], v[130:133], v[170:173], v[42:45]
	v_mfma_f32_16x16x32_bf16 v[34:37], v[138:141], v[170:173], v[34:37]
	v_mfma_f32_16x16x32_bf16 v[26:29], v[130:133], v[166:169], v[26:29]
	v_mfma_f32_16x16x32_bf16 v[18:21], v[138:141], v[166:169], v[18:21]
	v_mfma_f32_16x16x32_bf16 v[6:9], v[130:133], v[162:165], v[6:9]
	v_mfma_f32_16x16x32_bf16 v[2:5], v[138:141], v[162:165], v[2:5]
	v_mfma_f32_16x16x32_bf16 v[58:61], v[134:137], v[190:193], v[58:61]
	v_mfma_f32_16x16x32_bf16 v[50:53], v[142:145], v[190:193], v[50:53]
	v_mfma_f32_16x16x32_bf16 v[42:45], v[134:137], v[186:189], v[42:45]
	v_mfma_f32_16x16x32_bf16 v[34:37], v[142:145], v[186:189], v[34:37]
	v_mfma_f32_16x16x32_bf16 v[26:29], v[134:137], v[182:185], v[26:29]
	v_mfma_f32_16x16x32_bf16 v[18:21], v[142:145], v[182:185], v[18:21]
	v_mfma_f32_16x16x32_bf16 v[6:9], v[134:137], v[178:181], v[6:9]
	v_mfma_f32_16x16x32_bf16 v[2:5], v[142:145], v[178:181], v[2:5]
.LBB0_180:
	s_and_b64 vcc, s[46:47], s[86:87]
	v_cndmask_b32_e64 v131, v233, 0, vcc
	v_cndmask_b32_e32 v130, v232, v198, vcc
	v_lshl_add_u64 v[246:247], s[84:85], 0, v[130:131]
	s_barrier
	v_add_u32_e32 v130, 0x18000, v243
	v_add_u32_e32 v142, 0x1c000, v243
	ds_read_b128 v[146:149], v130
	ds_read_b128 v[150:153], v130 offset:1024
	ds_read_b128 v[154:157], v130 offset:2048
	ds_read_b128 v[158:161], v130 offset:3072
	ds_read_b128 v[130:133], v142
	ds_read_b128 v[134:137], v142 offset:1024
	ds_read_b128 v[138:141], v142 offset:2048
	ds_read_b128 v[142:145], v142 offset:3072
	s_mov_b32 m0, s14
	v_lshl_add_u64 v[248:249], v[246:247], 0, v[194:195]
	s_waitcnt lgkmcnt(0)
	ds_read_b128 v[174:177], v244 offset:32768
	ds_read_b128 v[190:193], v244 offset:33792
	ds_read_b128 v[170:173], v244 offset:34816
	ds_read_b128 v[186:189], v244 offset:35840
	ds_read_b128 v[166:169], v244 offset:36864
	ds_read_b128 v[182:185], v244 offset:37888
	ds_read_b128 v[162:165], v244 offset:38912
	ds_read_b128 v[178:181], v244 offset:39936
	s_mov_b32 m0, s13
	s_nop 0
	global_load_lds_dwordx4 v196, s[98:99]
	s_mov_b32 m0, s14
	s_nop 0
	global_load_lds_dwordx4 v[248:249], off
	v_lshl_add_u64 v[246:247], v[246:247], 0, v[196:197]
	s_mov_b32 m0, s15
	s_nop 0
	global_load_lds_dwordx4 v[246:247], off
	s_waitcnt vmcnt(8) lgkmcnt(0)
	s_barrier
	v_mfma_f32_16x16x32_bf16 v[118:121], v[146:149], v[174:177], v[118:121]
	v_mfma_f32_16x16x32_bf16 v[126:129], v[154:157], v[174:177], v[126:129]
	v_mfma_f32_16x16x32_bf16 v[102:105], v[146:149], v[170:173], v[102:105]
	v_mfma_f32_16x16x32_bf16 v[110:113], v[154:157], v[170:173], v[110:113]
	v_mfma_f32_16x16x32_bf16 v[86:89], v[146:149], v[166:169], v[86:89]
	v_mfma_f32_16x16x32_bf16 v[94:97], v[154:157], v[166:169], v[94:97]
	v_mfma_f32_16x16x32_bf16 v[70:73], v[146:149], v[162:165], v[70:73]
	v_mfma_f32_16x16x32_bf16 v[78:81], v[154:157], v[162:165], v[78:81]
	v_mfma_f32_16x16x32_bf16 v[118:121], v[150:153], v[190:193], v[118:121]
	v_mfma_f32_16x16x32_bf16 v[126:129], v[158:161], v[190:193], v[126:129]
	v_mfma_f32_16x16x32_bf16 v[102:105], v[150:153], v[186:189], v[102:105]
	v_mfma_f32_16x16x32_bf16 v[110:113], v[158:161], v[186:189], v[110:113]
	v_mfma_f32_16x16x32_bf16 v[86:89], v[150:153], v[182:185], v[86:89]
	v_mfma_f32_16x16x32_bf16 v[94:97], v[158:161], v[182:185], v[94:97]
	v_mfma_f32_16x16x32_bf16 v[70:73], v[150:153], v[178:181], v[70:73]
	v_mfma_f32_16x16x32_bf16 v[78:81], v[158:161], v[178:181], v[78:81]
	v_mfma_f32_16x16x32_bf16 v[122:125], v[130:133], v[174:177], v[122:125]
	v_mfma_f32_16x16x32_bf16 v[114:117], v[138:141], v[174:177], v[114:117]
	v_mfma_f32_16x16x32_bf16 v[106:109], v[130:133], v[170:173], v[106:109]
	v_mfma_f32_16x16x32_bf16 v[98:101], v[138:141], v[170:173], v[98:101]
	v_mfma_f32_16x16x32_bf16 v[90:93], v[130:133], v[166:169], v[90:93]
	v_mfma_f32_16x16x32_bf16 v[82:85], v[138:141], v[166:169], v[82:85]
	v_mfma_f32_16x16x32_bf16 v[74:77], v[130:133], v[162:165], v[74:77]
	v_mfma_f32_16x16x32_bf16 v[66:69], v[138:141], v[162:165], v[66:69]
	v_mfma_f32_16x16x32_bf16 v[122:125], v[134:137], v[190:193], v[122:125]
	v_mfma_f32_16x16x32_bf16 v[114:117], v[142:145], v[190:193], v[114:117]
	v_mfma_f32_16x16x32_bf16 v[106:109], v[134:137], v[186:189], v[106:109]
	v_mfma_f32_16x16x32_bf16 v[98:101], v[142:145], v[186:189], v[98:101]
	v_mfma_f32_16x16x32_bf16 v[90:93], v[134:137], v[182:185], v[90:93]
	v_mfma_f32_16x16x32_bf16 v[82:85], v[142:145], v[182:185], v[82:85]
	v_mfma_f32_16x16x32_bf16 v[74:77], v[134:137], v[178:181], v[74:77]
	v_mfma_f32_16x16x32_bf16 v[66:69], v[142:145], v[178:181], v[66:69]
	s_barrier
	s_and_b64 vcc, exec, s[48:49]
	s_cbranch_vccnz .LBB0_182
	ds_read_b128 v[174:177], v244 offset:49152
	ds_read_b128 v[190:193], v244 offset:50176
	ds_read_b128 v[170:173], v244 offset:51200
	ds_read_b128 v[186:189], v244 offset:52224
	ds_read_b128 v[166:169], v244 offset:53248
	ds_read_b128 v[182:185], v244 offset:54272
	ds_read_b128 v[162:165], v244 offset:55296
	ds_read_b128 v[178:181], v244 offset:56320
.LBB0_182:
	s_add_u32 s86, s82, 0x120000
	s_addc_u32 s87, s83, 0
	s_add_u32 s84, s84, 0x230000
	s_addc_u32 s85, s85, 0
	s_mov_b32 m0, s17
	s_add_u32 s82, s82, 0x124000
	global_load_lds_dwordx4 v194, s[86:87]
	s_mov_b32 m0, s54
	s_addc_u32 s83, s83, 0
	global_load_lds_dwordx4 v196, s[86:87]
	s_mov_b32 m0, s89
	s_and_b64 vcc, exec, s[48:49]
	global_load_lds_dwordx4 v194, s[82:83]
	s_mov_b32 m0, s90
	s_nop 0
	global_load_lds_dwordx4 v196, s[82:83]
	s_mov_b32 m0, s55
	s_nop 0
	global_load_lds_dwordx4 v194, s[84:85]
	s_mov_b64 s[100:101], s[84:85]
	s_waitcnt vmcnt(7) lgkmcnt(0)
	s_barrier
	s_cbranch_vccnz .LBB0_175
	s_waitcnt lgkmcnt(0)
	v_mfma_f32_16x16x32_bf16 v[54:57], v[146:149], v[174:177], v[54:57]
	v_mfma_f32_16x16x32_bf16 v[62:65], v[154:157], v[174:177], v[62:65]
	v_mfma_f32_16x16x32_bf16 v[38:41], v[146:149], v[170:173], v[38:41]
	v_mfma_f32_16x16x32_bf16 v[46:49], v[154:157], v[170:173], v[46:49]
	v_mfma_f32_16x16x32_bf16 v[22:25], v[146:149], v[166:169], v[22:25]
	v_mfma_f32_16x16x32_bf16 v[30:33], v[154:157], v[166:169], v[30:33]
	v_mfma_f32_16x16x32_bf16 v[10:13], v[146:149], v[162:165], v[10:13]
	v_mfma_f32_16x16x32_bf16 v[14:17], v[154:157], v[162:165], v[14:17]
	v_mfma_f32_16x16x32_bf16 v[54:57], v[150:153], v[190:193], v[54:57]
	v_mfma_f32_16x16x32_bf16 v[62:65], v[158:161], v[190:193], v[62:65]
	v_mfma_f32_16x16x32_bf16 v[38:41], v[150:153], v[186:189], v[38:41]
	v_mfma_f32_16x16x32_bf16 v[46:49], v[158:161], v[186:189], v[46:49]
	v_mfma_f32_16x16x32_bf16 v[22:25], v[150:153], v[182:185], v[22:25]
	v_mfma_f32_16x16x32_bf16 v[30:33], v[158:161], v[182:185], v[30:33]
	v_mfma_f32_16x16x32_bf16 v[10:13], v[150:153], v[178:181], v[10:13]
	v_mfma_f32_16x16x32_bf16 v[14:17], v[158:161], v[178:181], v[14:17]
	v_mfma_f32_16x16x32_bf16 v[58:61], v[130:133], v[174:177], v[58:61]
	v_mfma_f32_16x16x32_bf16 v[50:53], v[138:141], v[174:177], v[50:53]
	v_mfma_f32_16x16x32_bf16 v[42:45], v[130:133], v[170:173], v[42:45]
	v_mfma_f32_16x16x32_bf16 v[34:37], v[138:141], v[170:173], v[34:37]
	v_mfma_f32_16x16x32_bf16 v[26:29], v[130:133], v[166:169], v[26:29]
	v_mfma_f32_16x16x32_bf16 v[18:21], v[138:141], v[166:169], v[18:21]
	v_mfma_f32_16x16x32_bf16 v[6:9], v[130:133], v[162:165], v[6:9]
	v_mfma_f32_16x16x32_bf16 v[2:5], v[138:141], v[162:165], v[2:5]
	v_mfma_f32_16x16x32_bf16 v[58:61], v[134:137], v[190:193], v[58:61]
	v_mfma_f32_16x16x32_bf16 v[50:53], v[142:145], v[190:193], v[50:53]
	v_mfma_f32_16x16x32_bf16 v[42:45], v[134:137], v[186:189], v[42:45]
	v_mfma_f32_16x16x32_bf16 v[34:37], v[142:145], v[186:189], v[34:37]
	v_mfma_f32_16x16x32_bf16 v[26:29], v[134:137], v[182:185], v[26:29]
	v_mfma_f32_16x16x32_bf16 v[18:21], v[142:145], v[182:185], v[18:21]
	v_mfma_f32_16x16x32_bf16 v[6:9], v[134:137], v[178:181], v[6:9]
	v_mfma_f32_16x16x32_bf16 v[2:5], v[142:145], v[178:181], v[2:5]
	s_branch .LBB0_175

.LBB0_559:
	ds_read_b128 v[146:149], v227
	ds_read_b128 v[150:153], v227 offset:1024
	ds_read_b128 v[154:157], v227 offset:2048
	ds_read_b128 v[158:161], v227 offset:3072
	ds_read_b128 v[130:133], v228
	ds_read_b128 v[134:137], v228 offset:1024
	ds_read_b128 v[138:141], v228 offset:2048
	ds_read_b128 v[142:145], v228 offset:3072
	v_lshl_add_u64 v[234:235], v[216:217], 0, s[58:59]
	s_add_i32 m0, s8, 0xc000
	s_waitcnt lgkmcnt(0)
	ds_read_b128 v[174:177], v229
	ds_read_b128 v[190:193], v229 offset:1024
	ds_read_b128 v[170:173], v229 offset:2048
	ds_read_b128 v[186:189], v229 offset:3072
	ds_read_b128 v[166:169], v229 offset:4096
	ds_read_b128 v[182:185], v229 offset:5120
	ds_read_b128 v[162:165], v229 offset:6144
	ds_read_b128 v[178:181], v229 offset:7168
	s_mov_b32 m0, s67
	s_nop 0
	global_load_lds_dwordx4 v196, s[100:101]
	s_add_i32 m0, s8, 0xc000
	s_nop 0
	global_load_lds_dwordx4 v[234:235], off
	v_lshl_add_u64 v[234:235], v[218:219], 0, s[58:59]
	s_add_i32 m0, s8, 0xe000
	s_nop 0
	global_load_lds_dwordx4 v[234:235], off
	s_waitcnt vmcnt(8) lgkmcnt(0)
	s_barrier
	v_mfma_f32_16x16x32_bf16 v[126:129], v[146:149], v[174:177], v[126:129]
	v_mfma_f32_16x16x32_bf16 v[122:125], v[154:157], v[174:177], v[122:125]
	v_mfma_f32_16x16x32_bf16 v[110:113], v[146:149], v[170:173], v[110:113]
	v_mfma_f32_16x16x32_bf16 v[106:109], v[154:157], v[170:173], v[106:109]
	v_mfma_f32_16x16x32_bf16 v[94:97], v[146:149], v[166:169], v[94:97]
	v_mfma_f32_16x16x32_bf16 v[90:93], v[154:157], v[166:169], v[90:93]
	v_mfma_f32_16x16x32_bf16 v[78:81], v[146:149], v[162:165], v[78:81]
	v_mfma_f32_16x16x32_bf16 v[74:77], v[154:157], v[162:165], v[74:77]
	v_mfma_f32_16x16x32_bf16 v[126:129], v[150:153], v[190:193], v[126:129]
	v_mfma_f32_16x16x32_bf16 v[122:125], v[158:161], v[190:193], v[122:125]
	v_mfma_f32_16x16x32_bf16 v[110:113], v[150:153], v[186:189], v[110:113]
	v_mfma_f32_16x16x32_bf16 v[106:109], v[158:161], v[186:189], v[106:109]
	v_mfma_f32_16x16x32_bf16 v[94:97], v[150:153], v[182:185], v[94:97]
	v_mfma_f32_16x16x32_bf16 v[90:93], v[158:161], v[182:185], v[90:93]
	v_mfma_f32_16x16x32_bf16 v[78:81], v[150:153], v[178:181], v[78:81]
	v_mfma_f32_16x16x32_bf16 v[74:77], v[158:161], v[178:181], v[74:77]
	v_mfma_f32_16x16x32_bf16 v[118:121], v[130:133], v[174:177], v[118:121]
	v_mfma_f32_16x16x32_bf16 v[114:117], v[138:141], v[174:177], v[114:117]
	v_mfma_f32_16x16x32_bf16 v[102:105], v[130:133], v[170:173], v[102:105]
	v_mfma_f32_16x16x32_bf16 v[98:101], v[138:141], v[170:173], v[98:101]
	v_mfma_f32_16x16x32_bf16 v[86:89], v[130:133], v[166:169], v[86:89]
	v_mfma_f32_16x16x32_bf16 v[82:85], v[138:141], v[166:169], v[82:85]
	v_mfma_f32_16x16x32_bf16 v[70:73], v[130:133], v[162:165], v[70:73]
	v_mfma_f32_16x16x32_bf16 v[66:69], v[138:141], v[162:165], v[66:69]
	v_mfma_f32_16x16x32_bf16 v[118:121], v[134:137], v[190:193], v[118:121]
	v_mfma_f32_16x16x32_bf16 v[114:117], v[142:145], v[190:193], v[114:117]
	v_mfma_f32_16x16x32_bf16 v[102:105], v[134:137], v[186:189], v[102:105]
	v_mfma_f32_16x16x32_bf16 v[98:101], v[142:145], v[186:189], v[98:101]
	v_mfma_f32_16x16x32_bf16 v[86:89], v[134:137], v[182:185], v[86:89]
	v_mfma_f32_16x16x32_bf16 v[82:85], v[142:145], v[182:185], v[82:85]
	v_mfma_f32_16x16x32_bf16 v[70:73], v[134:137], v[178:181], v[70:73]
	v_mfma_f32_16x16x32_bf16 v[66:69], v[142:145], v[178:181], v[66:69]
	s_barrier
	v_cmp_ne_u32_e64 s[42:43], 1, v233
	s_andn2_b64 vcc, exec, s[44:45]
	s_cbranch_vccnz .LBB0_561
	ds_read_b128 v[174:177], v229 offset:16384
	ds_read_b128 v[190:193], v229 offset:17408
	ds_read_b128 v[170:173], v229 offset:18432
	ds_read_b128 v[186:189], v229 offset:19456
	ds_read_b128 v[166:169], v229 offset:20480
	ds_read_b128 v[182:185], v229 offset:21504
	ds_read_b128 v[162:165], v229 offset:22528
	ds_read_b128 v[178:181], v229 offset:23552
.LBB0_561:
	s_add_u32 s60, s56, s58
	s_addc_u32 s61, s57, s59
	s_add_u32 s62, s60, 0x440000
	s_addc_u32 s63, s61, 0
	s_cmp_eq_u32 s58, 0x3fc0000
	s_cselect_b64 s[68:69], -1, 0
	s_and_b64 s[60:61], s[68:69], exec
	s_cselect_b32 s61, s37, s72
	s_cselect_b32 s60, s47, s53
	s_mov_b32 m0, s9
	s_cselect_b32 s63, s1, s63
	s_cselect_b32 s62, s24, s62
	s_add_u32 s74, s60, 0x4000
	global_load_lds_dwordx4 v194, s[60:61]
	s_mov_b32 m0, s10
	s_addc_u32 s75, s61, 0
	global_load_lds_dwordx4 v196, s[60:61]
	s_mov_b32 m0, s11
	s_and_b64 vcc, exec, s[42:43]
	global_load_lds_dwordx4 v194, s[74:75]
	s_mov_b32 m0, s12
	s_nop 0
	global_load_lds_dwordx4 v196, s[74:75]
	s_mov_b32 m0, s8
	s_nop 0
	global_load_lds_dwordx4 v194, s[62:63]
	s_mov_b64 s[98:99], s[62:63]
	s_waitcnt vmcnt(7) lgkmcnt(0)
	s_barrier
	s_cbranch_vccnz .LBB0_563
	s_waitcnt lgkmcnt(0)
	v_mfma_f32_16x16x32_bf16 v[62:65], v[146:149], v[174:177], v[62:65]
	v_mfma_f32_16x16x32_bf16 v[58:61], v[154:157], v[174:177], v[58:61]
	v_mfma_f32_16x16x32_bf16 v[46:49], v[146:149], v[170:173], v[46:49]
	v_mfma_f32_16x16x32_bf16 v[42:45], v[154:157], v[170:173], v[42:45]
	v_mfma_f32_16x16x32_bf16 v[30:33], v[146:149], v[166:169], v[30:33]
	v_mfma_f32_16x16x32_bf16 v[26:29], v[154:157], v[166:169], v[26:29]
	v_mfma_f32_16x16x32_bf16 v[14:17], v[146:149], v[162:165], v[14:17]
	v_mfma_f32_16x16x32_bf16 v[10:13], v[154:157], v[162:165], v[10:13]
	v_mfma_f32_16x16x32_bf16 v[62:65], v[150:153], v[190:193], v[62:65]
	v_mfma_f32_16x16x32_bf16 v[58:61], v[158:161], v[190:193], v[58:61]
	v_mfma_f32_16x16x32_bf16 v[46:49], v[150:153], v[186:189], v[46:49]
	v_mfma_f32_16x16x32_bf16 v[42:45], v[158:161], v[186:189], v[42:45]
	v_mfma_f32_16x16x32_bf16 v[30:33], v[150:153], v[182:185], v[30:33]
	v_mfma_f32_16x16x32_bf16 v[26:29], v[158:161], v[182:185], v[26:29]
	v_mfma_f32_16x16x32_bf16 v[14:17], v[150:153], v[178:181], v[14:17]
	v_mfma_f32_16x16x32_bf16 v[10:13], v[158:161], v[178:181], v[10:13]
	v_mfma_f32_16x16x32_bf16 v[54:57], v[130:133], v[174:177], v[54:57]
	v_mfma_f32_16x16x32_bf16 v[50:53], v[138:141], v[174:177], v[50:53]
	v_mfma_f32_16x16x32_bf16 v[38:41], v[130:133], v[170:173], v[38:41]
	v_mfma_f32_16x16x32_bf16 v[34:37], v[138:141], v[170:173], v[34:37]
	v_mfma_f32_16x16x32_bf16 v[22:25], v[130:133], v[166:169], v[22:25]
	v_mfma_f32_16x16x32_bf16 v[18:21], v[138:141], v[166:169], v[18:21]
	v_mfma_f32_16x16x32_bf16 v[6:9], v[130:133], v[162:165], v[6:9]
	v_mfma_f32_16x16x32_bf16 v[2:5], v[138:141], v[162:165], v[2:5]
	v_mfma_f32_16x16x32_bf16 v[54:57], v[134:137], v[190:193], v[54:57]
	v_mfma_f32_16x16x32_bf16 v[50:53], v[142:145], v[190:193], v[50:53]
	v_mfma_f32_16x16x32_bf16 v[38:41], v[134:137], v[186:189], v[38:41]
	v_mfma_f32_16x16x32_bf16 v[34:37], v[142:145], v[186:189], v[34:37]
	v_mfma_f32_16x16x32_bf16 v[22:25], v[134:137], v[182:185], v[22:25]
	v_mfma_f32_16x16x32_bf16 v[18:21], v[142:145], v[182:185], v[18:21]
	v_mfma_f32_16x16x32_bf16 v[6:9], v[134:137], v[178:181], v[6:9]
	v_mfma_f32_16x16x32_bf16 v[2:5], v[142:145], v[178:181], v[2:5]
.LBB0_563:
	s_and_b64 vcc, s[40:41], s[68:69]
	v_cndmask_b32_e64 v131, v215, 0, vcc
	v_cndmask_b32_e32 v130, v214, v198, vcc
	v_lshl_add_u64 v[234:235], s[62:63], 0, v[130:131]
	s_barrier
	v_add_u32_e32 v130, 0x18000, v226
	v_add_u32_e32 v142, 0x1c000, v226
	ds_read_b128 v[146:149], v130
	ds_read_b128 v[150:153], v130 offset:1024
	ds_read_b128 v[154:157], v130 offset:2048
	ds_read_b128 v[158:161], v130 offset:3072
	ds_read_b128 v[130:133], v142
	ds_read_b128 v[134:137], v142 offset:1024
	ds_read_b128 v[138:141], v142 offset:2048
	ds_read_b128 v[142:145], v142 offset:3072
	s_mov_b32 m0, s14
	v_lshl_add_u64 v[236:237], v[234:235], 0, v[194:195]
	s_waitcnt lgkmcnt(0)
	ds_read_b128 v[174:177], v229 offset:32768
	ds_read_b128 v[190:193], v229 offset:33792
	ds_read_b128 v[170:173], v229 offset:34816
	ds_read_b128 v[186:189], v229 offset:35840
	ds_read_b128 v[166:169], v229 offset:36864
	ds_read_b128 v[182:185], v229 offset:37888
	ds_read_b128 v[162:165], v229 offset:38912
	ds_read_b128 v[178:181], v229 offset:39936
	s_mov_b32 m0, s13
	s_nop 0
	global_load_lds_dwordx4 v196, s[98:99]
	s_mov_b32 m0, s14
	s_nop 0
	global_load_lds_dwordx4 v[236:237], off
	v_lshl_add_u64 v[234:235], v[234:235], 0, v[196:197]
	s_mov_b32 m0, s15
	s_nop 0
	global_load_lds_dwordx4 v[234:235], off
	s_waitcnt vmcnt(8) lgkmcnt(0)
	s_barrier
	v_mfma_f32_16x16x32_bf16 v[126:129], v[146:149], v[174:177], v[126:129]
	v_mfma_f32_16x16x32_bf16 v[122:125], v[154:157], v[174:177], v[122:125]
	v_mfma_f32_16x16x32_bf16 v[110:113], v[146:149], v[170:173], v[110:113]
	v_mfma_f32_16x16x32_bf16 v[106:109], v[154:157], v[170:173], v[106:109]
	v_mfma_f32_16x16x32_bf16 v[94:97], v[146:149], v[166:169], v[94:97]
	v_mfma_f32_16x16x32_bf16 v[90:93], v[154:157], v[166:169], v[90:93]
	v_mfma_f32_16x16x32_bf16 v[78:81], v[146:149], v[162:165], v[78:81]
	v_mfma_f32_16x16x32_bf16 v[74:77], v[154:157], v[162:165], v[74:77]
	v_mfma_f32_16x16x32_bf16 v[126:129], v[150:153], v[190:193], v[126:129]
	v_mfma_f32_16x16x32_bf16 v[122:125], v[158:161], v[190:193], v[122:125]
	v_mfma_f32_16x16x32_bf16 v[110:113], v[150:153], v[186:189], v[110:113]
	v_mfma_f32_16x16x32_bf16 v[106:109], v[158:161], v[186:189], v[106:109]
	v_mfma_f32_16x16x32_bf16 v[94:97], v[150:153], v[182:185], v[94:97]
	v_mfma_f32_16x16x32_bf16 v[90:93], v[158:161], v[182:185], v[90:93]
	v_mfma_f32_16x16x32_bf16 v[78:81], v[150:153], v[178:181], v[78:81]
	v_mfma_f32_16x16x32_bf16 v[74:77], v[158:161], v[178:181], v[74:77]
	v_mfma_f32_16x16x32_bf16 v[118:121], v[130:133], v[174:177], v[118:121]
	v_mfma_f32_16x16x32_bf16 v[114:117], v[138:141], v[174:177], v[114:117]
	v_mfma_f32_16x16x32_bf16 v[102:105], v[130:133], v[170:173], v[102:105]
	v_mfma_f32_16x16x32_bf16 v[98:101], v[138:141], v[170:173], v[98:101]
	v_mfma_f32_16x16x32_bf16 v[86:89], v[130:133], v[166:169], v[86:89]
	v_mfma_f32_16x16x32_bf16 v[82:85], v[138:141], v[166:169], v[82:85]
	v_mfma_f32_16x16x32_bf16 v[70:73], v[130:133], v[162:165], v[70:73]
	v_mfma_f32_16x16x32_bf16 v[66:69], v[138:141], v[162:165], v[66:69]
	v_mfma_f32_16x16x32_bf16 v[118:121], v[134:137], v[190:193], v[118:121]
	v_mfma_f32_16x16x32_bf16 v[114:117], v[142:145], v[190:193], v[114:117]
	v_mfma_f32_16x16x32_bf16 v[102:105], v[134:137], v[186:189], v[102:105]
	v_mfma_f32_16x16x32_bf16 v[98:101], v[142:145], v[186:189], v[98:101]
	v_mfma_f32_16x16x32_bf16 v[86:89], v[134:137], v[182:185], v[86:89]
	v_mfma_f32_16x16x32_bf16 v[82:85], v[142:145], v[182:185], v[82:85]
	v_mfma_f32_16x16x32_bf16 v[70:73], v[134:137], v[178:181], v[70:73]
	v_mfma_f32_16x16x32_bf16 v[66:69], v[142:145], v[178:181], v[66:69]
	s_barrier
	s_and_b64 vcc, exec, s[42:43]
	s_cbranch_vccnz .LBB0_565
	ds_read_b128 v[174:177], v229 offset:49152
	ds_read_b128 v[190:193], v229 offset:50176
	ds_read_b128 v[170:173], v229 offset:51200
	ds_read_b128 v[186:189], v229 offset:52224
	ds_read_b128 v[166:169], v229 offset:53248
	ds_read_b128 v[182:185], v229 offset:54272
	ds_read_b128 v[162:165], v229 offset:55296
	ds_read_b128 v[178:181], v229 offset:56320
.LBB0_565:
	s_add_u32 s68, s60, 0x40000
	s_addc_u32 s69, s61, 0
	s_add_u32 s62, s62, 0x220000
	s_addc_u32 s63, s63, 0
	s_mov_b32 m0, s17
	s_add_u32 s60, s60, 0x44000
	global_load_lds_dwordx4 v194, s[68:69]
	s_mov_b32 m0, s54
	s_addc_u32 s61, s61, 0
	global_load_lds_dwordx4 v196, s[68:69]
	s_mov_b32 m0, s70
	s_and_b64 vcc, exec, s[42:43]
	global_load_lds_dwordx4 v194, s[60:61]
	s_mov_b32 m0, s71
	s_nop 0
	global_load_lds_dwordx4 v196, s[60:61]
	s_mov_b32 m0, s55
	s_nop 0
	global_load_lds_dwordx4 v194, s[62:63]
	s_mov_b64 s[100:101], s[62:63]
	s_waitcnt vmcnt(7) lgkmcnt(0)
	s_barrier
	s_cbranch_vccnz .LBB0_558
	s_waitcnt lgkmcnt(0)
	v_mfma_f32_16x16x32_bf16 v[62:65], v[146:149], v[174:177], v[62:65]
	v_mfma_f32_16x16x32_bf16 v[58:61], v[154:157], v[174:177], v[58:61]
	v_mfma_f32_16x16x32_bf16 v[46:49], v[146:149], v[170:173], v[46:49]
	v_mfma_f32_16x16x32_bf16 v[42:45], v[154:157], v[170:173], v[42:45]
	v_mfma_f32_16x16x32_bf16 v[30:33], v[146:149], v[166:169], v[30:33]
	v_mfma_f32_16x16x32_bf16 v[26:29], v[154:157], v[166:169], v[26:29]
	v_mfma_f32_16x16x32_bf16 v[14:17], v[146:149], v[162:165], v[14:17]
	v_mfma_f32_16x16x32_bf16 v[10:13], v[154:157], v[162:165], v[10:13]
	v_mfma_f32_16x16x32_bf16 v[62:65], v[150:153], v[190:193], v[62:65]
	v_mfma_f32_16x16x32_bf16 v[58:61], v[158:161], v[190:193], v[58:61]
	v_mfma_f32_16x16x32_bf16 v[46:49], v[150:153], v[186:189], v[46:49]
	v_mfma_f32_16x16x32_bf16 v[42:45], v[158:161], v[186:189], v[42:45]
	v_mfma_f32_16x16x32_bf16 v[30:33], v[150:153], v[182:185], v[30:33]
	v_mfma_f32_16x16x32_bf16 v[26:29], v[158:161], v[182:185], v[26:29]
	v_mfma_f32_16x16x32_bf16 v[14:17], v[150:153], v[178:181], v[14:17]
	v_mfma_f32_16x16x32_bf16 v[10:13], v[158:161], v[178:181], v[10:13]
	v_mfma_f32_16x16x32_bf16 v[54:57], v[130:133], v[174:177], v[54:57]
	v_mfma_f32_16x16x32_bf16 v[50:53], v[138:141], v[174:177], v[50:53]
	v_mfma_f32_16x16x32_bf16 v[38:41], v[130:133], v[170:173], v[38:41]
	v_mfma_f32_16x16x32_bf16 v[34:37], v[138:141], v[170:173], v[34:37]
	v_mfma_f32_16x16x32_bf16 v[22:25], v[130:133], v[166:169], v[22:25]
	v_mfma_f32_16x16x32_bf16 v[18:21], v[138:141], v[166:169], v[18:21]
	v_mfma_f32_16x16x32_bf16 v[6:9], v[130:133], v[162:165], v[6:9]
	v_mfma_f32_16x16x32_bf16 v[2:5], v[138:141], v[162:165], v[2:5]
	v_mfma_f32_16x16x32_bf16 v[54:57], v[134:137], v[190:193], v[54:57]
	v_mfma_f32_16x16x32_bf16 v[50:53], v[142:145], v[190:193], v[50:53]
	v_mfma_f32_16x16x32_bf16 v[38:41], v[134:137], v[186:189], v[38:41]
	v_mfma_f32_16x16x32_bf16 v[34:37], v[142:145], v[186:189], v[34:37]
	v_mfma_f32_16x16x32_bf16 v[22:25], v[134:137], v[182:185], v[22:25]
	v_mfma_f32_16x16x32_bf16 v[18:21], v[142:145], v[182:185], v[18:21]
	v_mfma_f32_16x16x32_bf16 v[6:9], v[134:137], v[178:181], v[6:9]
	v_mfma_f32_16x16x32_bf16 v[2:5], v[142:145], v[178:181], v[2:5]
	s_branch .LBB0_558

.LBB0_761:
	ds_read_b128 v[130:133], v237
	ds_read_b128 v[134:137], v237 offset:1024
	ds_read_b128 v[138:141], v237 offset:2048
	ds_read_b128 v[142:145], v237 offset:3072
	ds_read_b128 v[146:149], v238
	ds_read_b128 v[150:153], v238 offset:1024
	ds_read_b128 v[154:157], v238 offset:2048
	ds_read_b128 v[158:161], v238 offset:3072
	s_add_u32 s48, s0, 0x21c000
	s_addc_u32 s49, s1, 0
	s_cmp_eq_u32 s67, 28
	s_cselect_b32 s42, s55, s62
	s_cselect_b32 s43, s29, s63
	s_cselect_b32 s52, s45, s48
	s_cselect_b32 s53, s31, s49
	s_add_u32 s50, s42, 0xe0000
	s_addc_u32 s51, s43, 0
	s_add_u32 s48, s52, 0x220000
	s_addc_u32 s49, s53, 0
	v_lshl_add_u64 v[208:209], s[0:1], 0, v[202:203]
	s_add_i32 m0, s9, 0xc000
	ds_read_b128 v[162:165], v239
	ds_read_b128 v[166:169], v239 offset:1024
	ds_read_b128 v[170:173], v239 offset:2048
	ds_read_b128 v[174:177], v239 offset:3072
	ds_read_b128 v[178:181], v239 offset:4096
	ds_read_b128 v[182:185], v239 offset:5120
	ds_read_b128 v[186:189], v239 offset:6144
	ds_read_b128 v[190:193], v239 offset:7168
	s_mov_b32 m0, s15
	s_nop 0
	global_load_lds_dwordx4 v196, s[100:101]
	s_add_i32 m0, s9, 0xc000
	s_nop 0
	global_load_lds_dwordx4 v[208:209], off
	v_lshl_add_u64 v[208:209], s[0:1], 0, v[200:201]
	s_add_i32 m0, s9, 0xe000
	s_nop 0
	global_load_lds_dwordx4 v[208:209], off
	s_waitcnt vmcnt(8) lgkmcnt(0)
	s_barrier
	v_mfma_f32_16x16x32_bf16 v[126:129], v[130:133], v[162:165], v[126:129]
	v_mfma_f32_16x16x32_bf16 v[122:125], v[138:141], v[162:165], v[122:125]
	v_mfma_f32_16x16x32_bf16 v[118:121], v[130:133], v[170:173], v[118:121]
	v_mfma_f32_16x16x32_bf16 v[114:117], v[138:141], v[170:173], v[114:117]
	v_mfma_f32_16x16x32_bf16 v[110:113], v[130:133], v[178:181], v[110:113]
	v_mfma_f32_16x16x32_bf16 v[106:109], v[138:141], v[178:181], v[106:109]
	v_mfma_f32_16x16x32_bf16 v[102:105], v[130:133], v[186:189], v[102:105]
	v_mfma_f32_16x16x32_bf16 v[98:101], v[138:141], v[186:189], v[98:101]
	v_mfma_f32_16x16x32_bf16 v[126:129], v[134:137], v[166:169], v[126:129]
	v_mfma_f32_16x16x32_bf16 v[122:125], v[142:145], v[166:169], v[122:125]
	v_mfma_f32_16x16x32_bf16 v[118:121], v[134:137], v[174:177], v[118:121]
	v_mfma_f32_16x16x32_bf16 v[114:117], v[142:145], v[174:177], v[114:117]
	v_mfma_f32_16x16x32_bf16 v[110:113], v[134:137], v[182:185], v[110:113]
	v_mfma_f32_16x16x32_bf16 v[106:109], v[142:145], v[182:185], v[106:109]
	v_mfma_f32_16x16x32_bf16 v[102:105], v[134:137], v[190:193], v[102:105]
	v_mfma_f32_16x16x32_bf16 v[98:101], v[142:145], v[190:193], v[98:101]
	v_mfma_f32_16x16x32_bf16 v[62:65], v[146:149], v[162:165], v[62:65]
	s_add_u32 s60, s52, 0x4000
	s_addc_u32 s61, s53, 0
	v_mfma_f32_16x16x32_bf16 v[58:61], v[154:157], v[162:165], v[58:61]
	v_mfma_f32_16x16x32_bf16 v[54:57], v[146:149], v[170:173], v[54:57]
	v_mfma_f32_16x16x32_bf16 v[50:53], v[154:157], v[170:173], v[50:53]
	v_mfma_f32_16x16x32_bf16 v[46:49], v[146:149], v[178:181], v[46:49]
	v_mfma_f32_16x16x32_bf16 v[42:45], v[154:157], v[178:181], v[42:45]
	v_mfma_f32_16x16x32_bf16 v[38:41], v[146:149], v[186:189], v[38:41]
	v_mfma_f32_16x16x32_bf16 v[34:37], v[154:157], v[186:189], v[34:37]
	v_mfma_f32_16x16x32_bf16 v[62:65], v[150:153], v[166:169], v[62:65]
	v_mfma_f32_16x16x32_bf16 v[58:61], v[158:161], v[166:169], v[58:61]
	v_mfma_f32_16x16x32_bf16 v[54:57], v[150:153], v[174:177], v[54:57]
	v_mfma_f32_16x16x32_bf16 v[50:53], v[158:161], v[174:177], v[50:53]
	v_mfma_f32_16x16x32_bf16 v[46:49], v[150:153], v[182:185], v[46:49]
	v_mfma_f32_16x16x32_bf16 v[42:45], v[158:161], v[182:185], v[42:45]
	v_mfma_f32_16x16x32_bf16 v[38:41], v[150:153], v[190:193], v[38:41]
	v_mfma_f32_16x16x32_bf16 v[34:37], v[158:161], v[190:193], v[34:37]
	s_barrier
	s_add_i32 s68, s16, s8
	s_mov_b32 m0, s68
	ds_read_b128 v[162:165], v239 offset:16384
	ds_read_b128 v[166:169], v239 offset:17408
	ds_read_b128 v[170:173], v239 offset:18432
	ds_read_b128 v[174:177], v239 offset:19456
	ds_read_b128 v[178:181], v239 offset:20480
	ds_read_b128 v[182:185], v239 offset:21504
	ds_read_b128 v[186:189], v239 offset:22528
	ds_read_b128 v[190:193], v239 offset:23552
	global_load_lds_dwordx4 v194, s[42:43]
	s_add_i32 m0, s68, 0x2000
	s_add_u32 s68, s42, 0x4000
	s_addc_u32 s69, s43, 0
	s_add_i32 s70, s17, s8
	global_load_lds_dwordx4 v196, s[42:43]
	s_mov_b32 m0, s70
	s_nop 0
	global_load_lds_dwordx4 v194, s[68:69]
	s_add_i32 m0, s70, 0x2000
	s_nop 0
	global_load_lds_dwordx4 v196, s[68:69]
	s_mov_b32 m0, s9
	s_nop 0
	global_load_lds_dwordx4 v194, s[52:53]
	s_mov_b64 s[98:99], s[52:53]
	s_waitcnt vmcnt(7) lgkmcnt(0)
	s_barrier
	v_mfma_f32_16x16x32_bf16 v[94:97], v[130:133], v[162:165], v[94:97]
	v_mfma_f32_16x16x32_bf16 v[90:93], v[138:141], v[162:165], v[90:93]
	v_mfma_f32_16x16x32_bf16 v[86:89], v[130:133], v[170:173], v[86:89]
	v_mfma_f32_16x16x32_bf16 v[82:85], v[138:141], v[170:173], v[82:85]
	v_mfma_f32_16x16x32_bf16 v[78:81], v[130:133], v[178:181], v[78:81]
	v_mfma_f32_16x16x32_bf16 v[74:77], v[138:141], v[178:181], v[74:77]
	v_mfma_f32_16x16x32_bf16 v[70:73], v[130:133], v[186:189], v[70:73]
	v_mfma_f32_16x16x32_bf16 v[66:69], v[138:141], v[186:189], v[66:69]
	v_mfma_f32_16x16x32_bf16 v[94:97], v[134:137], v[166:169], v[94:97]
	v_mfma_f32_16x16x32_bf16 v[90:93], v[142:145], v[166:169], v[90:93]
	v_mfma_f32_16x16x32_bf16 v[86:89], v[134:137], v[174:177], v[86:89]
	v_mfma_f32_16x16x32_bf16 v[82:85], v[142:145], v[174:177], v[82:85]
	v_mfma_f32_16x16x32_bf16 v[78:81], v[134:137], v[182:185], v[78:81]
	v_mfma_f32_16x16x32_bf16 v[74:77], v[142:145], v[182:185], v[74:77]
	v_mfma_f32_16x16x32_bf16 v[70:73], v[134:137], v[190:193], v[70:73]
	v_mfma_f32_16x16x32_bf16 v[66:69], v[142:145], v[190:193], v[66:69]
	v_mfma_f32_16x16x32_bf16 v[30:33], v[146:149], v[162:165], v[30:33]
	v_mfma_f32_16x16x32_bf16 v[26:29], v[154:157], v[162:165], v[26:29]
	v_mfma_f32_16x16x32_bf16 v[22:25], v[146:149], v[170:173], v[22:25]
	v_mfma_f32_16x16x32_bf16 v[18:21], v[154:157], v[170:173], v[18:21]
	v_mfma_f32_16x16x32_bf16 v[14:17], v[146:149], v[178:181], v[14:17]
	v_mfma_f32_16x16x32_bf16 v[10:13], v[154:157], v[178:181], v[10:13]
	v_mfma_f32_16x16x32_bf16 v[6:9], v[146:149], v[186:189], v[6:9]
	v_mfma_f32_16x16x32_bf16 v[2:5], v[154:157], v[186:189], v[2:5]
	v_mfma_f32_16x16x32_bf16 v[30:33], v[150:153], v[166:169], v[30:33]
	v_mfma_f32_16x16x32_bf16 v[26:29], v[158:161], v[166:169], v[26:29]
	v_mfma_f32_16x16x32_bf16 v[22:25], v[150:153], v[174:177], v[22:25]
	v_mfma_f32_16x16x32_bf16 v[18:21], v[158:161], v[174:177], v[18:21]
	v_mfma_f32_16x16x32_bf16 v[14:17], v[150:153], v[182:185], v[14:17]
	v_mfma_f32_16x16x32_bf16 v[10:13], v[158:161], v[182:185], v[10:13]
	v_mfma_f32_16x16x32_bf16 v[6:9], v[150:153], v[190:193], v[6:9]
	v_mfma_f32_16x16x32_bf16 v[2:5], v[158:161], v[190:193], v[2:5]
	s_barrier
	s_add_i32 s52, 0, 0x18000
	s_add_i32 s53, 0, 0x1c000
	v_add_u32_e32 v142, s52, v228
	v_add_u32_e32 v158, s53, v228
	ds_read_b128 v[130:133], v142
	ds_read_b128 v[134:137], v142 offset:1024
	ds_read_b128 v[138:141], v142 offset:2048
	ds_read_b128 v[142:145], v142 offset:3072
	ds_read_b128 v[146:149], v158
	ds_read_b128 v[150:153], v158 offset:1024
	ds_read_b128 v[154:157], v158 offset:2048
	ds_read_b128 v[158:161], v158 offset:3072
	s_mov_b32 m0, s11
	ds_read_b128 v[162:165], v239 offset:32768
	ds_read_b128 v[166:169], v239 offset:33792
	ds_read_b128 v[170:173], v239 offset:34816
	ds_read_b128 v[174:177], v239 offset:35840
	ds_read_b128 v[178:181], v239 offset:36864
	ds_read_b128 v[182:185], v239 offset:37888
	ds_read_b128 v[186:189], v239 offset:38912
	ds_read_b128 v[190:193], v239 offset:39936
	s_mov_b32 m0, s10
	s_nop 0
	global_load_lds_dwordx4 v196, s[98:99]
	s_mov_b32 m0, s11
	s_nop 0
	global_load_lds_dwordx4 v194, s[60:61]
	s_mov_b32 m0, s12
	s_nop 0
	global_load_lds_dwordx4 v196, s[60:61]
	s_waitcnt vmcnt(8) lgkmcnt(0)
	s_barrier
	v_mfma_f32_16x16x32_bf16 v[126:129], v[130:133], v[162:165], v[126:129]
	v_mfma_f32_16x16x32_bf16 v[122:125], v[138:141], v[162:165], v[122:125]
	v_mfma_f32_16x16x32_bf16 v[118:121], v[130:133], v[170:173], v[118:121]
	v_mfma_f32_16x16x32_bf16 v[114:117], v[138:141], v[170:173], v[114:117]
	v_mfma_f32_16x16x32_bf16 v[110:113], v[130:133], v[178:181], v[110:113]
	v_mfma_f32_16x16x32_bf16 v[106:109], v[138:141], v[178:181], v[106:109]
	v_mfma_f32_16x16x32_bf16 v[102:105], v[130:133], v[186:189], v[102:105]
	v_mfma_f32_16x16x32_bf16 v[98:101], v[138:141], v[186:189], v[98:101]
	v_mfma_f32_16x16x32_bf16 v[126:129], v[134:137], v[166:169], v[126:129]
	v_mfma_f32_16x16x32_bf16 v[122:125], v[142:145], v[166:169], v[122:125]
	v_mfma_f32_16x16x32_bf16 v[118:121], v[134:137], v[174:177], v[118:121]
	v_mfma_f32_16x16x32_bf16 v[114:117], v[142:145], v[174:177], v[114:117]
	v_mfma_f32_16x16x32_bf16 v[110:113], v[134:137], v[182:185], v[110:113]
	v_mfma_f32_16x16x32_bf16 v[106:109], v[142:145], v[182:185], v[106:109]
	v_mfma_f32_16x16x32_bf16 v[102:105], v[134:137], v[190:193], v[102:105]
	v_mfma_f32_16x16x32_bf16 v[98:101], v[142:145], v[190:193], v[98:101]
	v_mfma_f32_16x16x32_bf16 v[62:65], v[146:149], v[162:165], v[62:65]
	v_mfma_f32_16x16x32_bf16 v[58:61], v[154:157], v[162:165], v[58:61]
	v_mfma_f32_16x16x32_bf16 v[54:57], v[146:149], v[170:173], v[54:57]
	v_mfma_f32_16x16x32_bf16 v[50:53], v[154:157], v[170:173], v[50:53]
	v_mfma_f32_16x16x32_bf16 v[46:49], v[146:149], v[178:181], v[46:49]
	v_mfma_f32_16x16x32_bf16 v[42:45], v[154:157], v[178:181], v[42:45]
	v_mfma_f32_16x16x32_bf16 v[38:41], v[146:149], v[186:189], v[38:41]
	v_mfma_f32_16x16x32_bf16 v[34:37], v[154:157], v[186:189], v[34:37]
	v_mfma_f32_16x16x32_bf16 v[62:65], v[150:153], v[166:169], v[62:65]
	v_mfma_f32_16x16x32_bf16 v[58:61], v[158:161], v[166:169], v[58:61]
	v_mfma_f32_16x16x32_bf16 v[54:57], v[150:153], v[174:177], v[54:57]
	v_mfma_f32_16x16x32_bf16 v[50:53], v[158:161], v[174:177], v[50:53]
	v_mfma_f32_16x16x32_bf16 v[46:49], v[150:153], v[182:185], v[46:49]
	v_mfma_f32_16x16x32_bf16 v[42:45], v[158:161], v[182:185], v[42:45]
	v_mfma_f32_16x16x32_bf16 v[38:41], v[150:153], v[190:193], v[38:41]
	v_mfma_f32_16x16x32_bf16 v[34:37], v[158:161], v[190:193], v[34:37]
	s_barrier
	s_add_i32 s52, s52, s8
	s_mov_b32 m0, s52
	ds_read_b128 v[162:165], v239 offset:49152
	ds_read_b128 v[166:169], v239 offset:50176
	ds_read_b128 v[170:173], v239 offset:51200
	ds_read_b128 v[174:177], v239 offset:52224
	ds_read_b128 v[178:181], v239 offset:53248
	ds_read_b128 v[182:185], v239 offset:54272
	ds_read_b128 v[186:189], v239 offset:55296
	ds_read_b128 v[190:193], v239 offset:56320
	global_load_lds_dwordx4 v194, s[50:51]
	s_add_i32 m0, s52, 0x2000
	s_add_u32 s42, s42, 0xe4000
	v_lshl_add_u64 v[208:209], s[50:51], 0, v[196:197]
	s_addc_u32 s43, s43, 0
	s_add_i32 s50, s53, s8
	global_load_lds_dwordx4 v[208:209], off
	s_mov_b32 m0, s50
	s_nop 0
	global_load_lds_dwordx4 v194, s[42:43]
	s_add_i32 m0, s50, 0x2000
	s_nop 0
	global_load_lds_dwordx4 v196, s[42:43]
	s_mov_b32 m0, s14
	s_nop 0
	global_load_lds_dwordx4 v194, s[48:49]
	s_mov_b64 s[100:101], s[48:49]
	s_waitcnt vmcnt(7) lgkmcnt(0)
	s_barrier
	v_mfma_f32_16x16x32_bf16 v[94:97], v[130:133], v[162:165], v[94:97]
	v_mfma_f32_16x16x32_bf16 v[90:93], v[138:141], v[162:165], v[90:93]
	v_mfma_f32_16x16x32_bf16 v[86:89], v[130:133], v[170:173], v[86:89]
	v_mfma_f32_16x16x32_bf16 v[82:85], v[138:141], v[170:173], v[82:85]
	v_mfma_f32_16x16x32_bf16 v[78:81], v[130:133], v[178:181], v[78:81]
	v_mfma_f32_16x16x32_bf16 v[74:77], v[138:141], v[178:181], v[74:77]
	v_mfma_f32_16x16x32_bf16 v[70:73], v[130:133], v[186:189], v[70:73]
	v_mfma_f32_16x16x32_bf16 v[66:69], v[138:141], v[186:189], v[66:69]
	v_mfma_f32_16x16x32_bf16 v[94:97], v[134:137], v[166:169], v[94:97]
	v_mfma_f32_16x16x32_bf16 v[90:93], v[142:145], v[166:169], v[90:93]
	v_mfma_f32_16x16x32_bf16 v[86:89], v[134:137], v[174:177], v[86:89]
	v_mfma_f32_16x16x32_bf16 v[82:85], v[142:145], v[174:177], v[82:85]
	v_mfma_f32_16x16x32_bf16 v[78:81], v[134:137], v[182:185], v[78:81]
	v_mfma_f32_16x16x32_bf16 v[74:77], v[142:145], v[182:185], v[74:77]
	v_mfma_f32_16x16x32_bf16 v[70:73], v[134:137], v[190:193], v[70:73]
	v_mfma_f32_16x16x32_bf16 v[66:69], v[142:145], v[190:193], v[66:69]
	v_mfma_f32_16x16x32_bf16 v[30:33], v[146:149], v[162:165], v[30:33]
	v_mfma_f32_16x16x32_bf16 v[26:29], v[154:157], v[162:165], v[26:29]
	v_mfma_f32_16x16x32_bf16 v[22:25], v[146:149], v[170:173], v[22:25]
	v_mfma_f32_16x16x32_bf16 v[18:21], v[154:157], v[170:173], v[18:21]
	v_mfma_f32_16x16x32_bf16 v[14:17], v[146:149], v[178:181], v[14:17]
	v_mfma_f32_16x16x32_bf16 v[10:13], v[154:157], v[178:181], v[10:13]
	v_mfma_f32_16x16x32_bf16 v[6:9], v[146:149], v[186:189], v[6:9]
	v_mfma_f32_16x16x32_bf16 v[2:5], v[154:157], v[186:189], v[2:5]
	v_mfma_f32_16x16x32_bf16 v[30:33], v[150:153], v[166:169], v[30:33]
	v_mfma_f32_16x16x32_bf16 v[26:29], v[158:161], v[166:169], v[26:29]
	v_mfma_f32_16x16x32_bf16 v[22:25], v[150:153], v[174:177], v[22:25]
	v_mfma_f32_16x16x32_bf16 v[18:21], v[158:161], v[174:177], v[18:21]
	v_mfma_f32_16x16x32_bf16 v[14:17], v[150:153], v[182:185], v[14:17]
	v_mfma_f32_16x16x32_bf16 v[10:13], v[158:161], v[182:185], v[10:13]
	v_mfma_f32_16x16x32_bf16 v[6:9], v[150:153], v[190:193], v[6:9]
	v_mfma_f32_16x16x32_bf16 v[2:5], v[158:161], v[190:193], v[2:5]
	s_barrier
	s_add_i32 s67, s67, 2
	s_add_u32 s62, s62, 0x1c0000
	s_addc_u32 s63, s63, 0
	s_add_u32 s0, s0, 0x440000
	s_addc_u32 s1, s1, 0
	s_cmp_gt_u32 s67, 29
	s_cbranch_scc0 .LBB0_761
	s_and_b64 vcc, exec, s[26:27]
	s_cbranch_vccz .LBB0_764
	s_barrier

.LBB0_903:
	ds_read_b128 v[146:149], v225
	ds_read_b128 v[150:153], v225 offset:1024
	ds_read_b128 v[154:157], v225 offset:2048
	ds_read_b128 v[158:161], v225 offset:3072
	ds_read_b128 v[130:133], v227
	ds_read_b128 v[134:137], v227 offset:1024
	ds_read_b128 v[138:141], v227 offset:2048
	ds_read_b128 v[142:145], v227 offset:3072
	v_lshl_add_u64 v[234:235], v[210:211], 0, s[62:63]
	s_add_i32 m0, s8, 0xc000
	s_waitcnt lgkmcnt(0)
	ds_read_b128 v[174:177], v228
	ds_read_b128 v[190:193], v228 offset:1024
	ds_read_b128 v[170:173], v228 offset:2048
	ds_read_b128 v[186:189], v228 offset:3072
	ds_read_b128 v[166:169], v228 offset:4096
	ds_read_b128 v[182:185], v228 offset:5120
	ds_read_b128 v[162:165], v228 offset:6144
	ds_read_b128 v[178:181], v228 offset:7168
	s_mov_b32 m0, s31
	s_nop 0
	global_load_lds_dwordx4 v196, s[100:101]
	s_add_i32 m0, s8, 0xc000
	s_nop 0
	global_load_lds_dwordx4 v[234:235], off
	v_lshl_add_u64 v[234:235], v[212:213], 0, s[62:63]
	s_add_i32 m0, s8, 0xe000
	s_nop 0
	global_load_lds_dwordx4 v[234:235], off
	s_waitcnt vmcnt(8) lgkmcnt(0)
	s_barrier
	v_mfma_f32_16x16x32_bf16 v[126:129], v[146:149], v[174:177], v[126:129]
	v_mfma_f32_16x16x32_bf16 v[122:125], v[154:157], v[174:177], v[122:125]
	v_mfma_f32_16x16x32_bf16 v[118:121], v[146:149], v[170:173], v[118:121]
	v_mfma_f32_16x16x32_bf16 v[114:117], v[154:157], v[170:173], v[114:117]
	v_mfma_f32_16x16x32_bf16 v[110:113], v[146:149], v[166:169], v[110:113]
	v_mfma_f32_16x16x32_bf16 v[106:109], v[154:157], v[166:169], v[106:109]
	v_mfma_f32_16x16x32_bf16 v[102:105], v[146:149], v[162:165], v[102:105]
	v_mfma_f32_16x16x32_bf16 v[98:101], v[154:157], v[162:165], v[98:101]
	v_mfma_f32_16x16x32_bf16 v[126:129], v[150:153], v[190:193], v[126:129]
	v_mfma_f32_16x16x32_bf16 v[122:125], v[158:161], v[190:193], v[122:125]
	v_mfma_f32_16x16x32_bf16 v[118:121], v[150:153], v[186:189], v[118:121]
	v_mfma_f32_16x16x32_bf16 v[114:117], v[158:161], v[186:189], v[114:117]
	v_mfma_f32_16x16x32_bf16 v[110:113], v[150:153], v[182:185], v[110:113]
	v_mfma_f32_16x16x32_bf16 v[106:109], v[158:161], v[182:185], v[106:109]
	v_mfma_f32_16x16x32_bf16 v[102:105], v[150:153], v[178:181], v[102:105]
	v_mfma_f32_16x16x32_bf16 v[98:101], v[158:161], v[178:181], v[98:101]
	v_mfma_f32_16x16x32_bf16 v[94:97], v[130:133], v[174:177], v[94:97]
	v_mfma_f32_16x16x32_bf16 v[90:93], v[138:141], v[174:177], v[90:93]
	v_mfma_f32_16x16x32_bf16 v[86:89], v[130:133], v[170:173], v[86:89]
	v_mfma_f32_16x16x32_bf16 v[82:85], v[138:141], v[170:173], v[82:85]
	v_mfma_f32_16x16x32_bf16 v[78:81], v[130:133], v[166:169], v[78:81]
	v_mfma_f32_16x16x32_bf16 v[74:77], v[138:141], v[166:169], v[74:77]
	v_mfma_f32_16x16x32_bf16 v[70:73], v[130:133], v[162:165], v[70:73]
	v_mfma_f32_16x16x32_bf16 v[66:69], v[138:141], v[162:165], v[66:69]
	v_mfma_f32_16x16x32_bf16 v[94:97], v[134:137], v[190:193], v[94:97]
	v_mfma_f32_16x16x32_bf16 v[90:93], v[142:145], v[190:193], v[90:93]
	v_mfma_f32_16x16x32_bf16 v[86:89], v[134:137], v[186:189], v[86:89]
	v_mfma_f32_16x16x32_bf16 v[82:85], v[142:145], v[186:189], v[82:85]
	v_mfma_f32_16x16x32_bf16 v[78:81], v[134:137], v[182:185], v[78:81]
	v_mfma_f32_16x16x32_bf16 v[74:77], v[142:145], v[182:185], v[74:77]
	v_mfma_f32_16x16x32_bf16 v[70:73], v[134:137], v[178:181], v[70:73]
	v_mfma_f32_16x16x32_bf16 v[66:69], v[142:145], v[178:181], v[66:69]
	s_barrier
	v_cmp_ne_u32_e64 s[42:43], 1, v233
	s_andn2_b64 vcc, exec, s[44:45]
	s_cbranch_vccnz .LBB0_905
	ds_read_b128 v[174:177], v228 offset:16384
	ds_read_b128 v[190:193], v228 offset:17408
	ds_read_b128 v[170:173], v228 offset:18432
	ds_read_b128 v[186:189], v228 offset:19456
	ds_read_b128 v[166:169], v228 offset:20480
	ds_read_b128 v[182:185], v228 offset:21504
	ds_read_b128 v[162:165], v228 offset:22528
	ds_read_b128 v[178:181], v228 offset:23552
.LBB0_905:
	s_add_u32 s68, s0, s62
	s_addc_u32 s69, s1, s63
	s_add_u32 s70, s68, 0x440000
	s_addc_u32 s71, s69, 0
	s_cmp_eq_u32 s62, 0x3fc0000
	s_cselect_b64 s[72:73], -1, 0
	s_and_b64 s[68:69], s[72:73], exec
	s_cselect_b32 s69, s37, s77
	s_cselect_b32 s68, s75, s76
	s_mov_b32 m0, s9
	s_cselect_b32 s71, s35, s71
	s_cselect_b32 s70, s74, s70
	s_add_u32 s80, s68, 0x4000
	global_load_lds_dwordx4 v194, s[68:69]
	s_mov_b32 m0, s10
	s_addc_u32 s81, s69, 0
	global_load_lds_dwordx4 v196, s[68:69]
	s_mov_b32 m0, s11
	s_and_b64 vcc, exec, s[42:43]
	global_load_lds_dwordx4 v194, s[80:81]
	s_mov_b32 m0, s12
	s_nop 0
	global_load_lds_dwordx4 v196, s[80:81]
	s_mov_b32 m0, s8
	s_nop 0
	global_load_lds_dwordx4 v194, s[70:71]
	s_mov_b64 s[98:99], s[70:71]
	s_waitcnt vmcnt(7) lgkmcnt(0)
	s_barrier
	s_cbranch_vccnz .LBB0_907
	s_waitcnt lgkmcnt(0)
	v_mfma_f32_16x16x32_bf16 v[62:65], v[146:149], v[174:177], v[62:65]
	v_mfma_f32_16x16x32_bf16 v[58:61], v[154:157], v[174:177], v[58:61]
	v_mfma_f32_16x16x32_bf16 v[54:57], v[146:149], v[170:173], v[54:57]
	v_mfma_f32_16x16x32_bf16 v[50:53], v[154:157], v[170:173], v[50:53]
	v_mfma_f32_16x16x32_bf16 v[46:49], v[146:149], v[166:169], v[46:49]
	v_mfma_f32_16x16x32_bf16 v[42:45], v[154:157], v[166:169], v[42:45]
	v_mfma_f32_16x16x32_bf16 v[38:41], v[146:149], v[162:165], v[38:41]
	v_mfma_f32_16x16x32_bf16 v[34:37], v[154:157], v[162:165], v[34:37]
	v_mfma_f32_16x16x32_bf16 v[62:65], v[150:153], v[190:193], v[62:65]
	v_mfma_f32_16x16x32_bf16 v[58:61], v[158:161], v[190:193], v[58:61]
	v_mfma_f32_16x16x32_bf16 v[54:57], v[150:153], v[186:189], v[54:57]
	v_mfma_f32_16x16x32_bf16 v[50:53], v[158:161], v[186:189], v[50:53]
	v_mfma_f32_16x16x32_bf16 v[46:49], v[150:153], v[182:185], v[46:49]
	v_mfma_f32_16x16x32_bf16 v[42:45], v[158:161], v[182:185], v[42:45]
	v_mfma_f32_16x16x32_bf16 v[38:41], v[150:153], v[178:181], v[38:41]
	v_mfma_f32_16x16x32_bf16 v[34:37], v[158:161], v[178:181], v[34:37]
	v_mfma_f32_16x16x32_bf16 v[30:33], v[130:133], v[174:177], v[30:33]
	v_mfma_f32_16x16x32_bf16 v[26:29], v[138:141], v[174:177], v[26:29]
	v_mfma_f32_16x16x32_bf16 v[22:25], v[130:133], v[170:173], v[22:25]
	v_mfma_f32_16x16x32_bf16 v[18:21], v[138:141], v[170:173], v[18:21]
	v_mfma_f32_16x16x32_bf16 v[14:17], v[130:133], v[166:169], v[14:17]
	v_mfma_f32_16x16x32_bf16 v[10:13], v[138:141], v[166:169], v[10:13]
	v_mfma_f32_16x16x32_bf16 v[6:9], v[130:133], v[162:165], v[6:9]
	v_mfma_f32_16x16x32_bf16 v[2:5], v[138:141], v[162:165], v[2:5]
	v_mfma_f32_16x16x32_bf16 v[30:33], v[134:137], v[190:193], v[30:33]
	v_mfma_f32_16x16x32_bf16 v[26:29], v[142:145], v[190:193], v[26:29]
	v_mfma_f32_16x16x32_bf16 v[22:25], v[134:137], v[186:189], v[22:25]
	v_mfma_f32_16x16x32_bf16 v[18:21], v[142:145], v[186:189], v[18:21]
	v_mfma_f32_16x16x32_bf16 v[14:17], v[134:137], v[182:185], v[14:17]
	v_mfma_f32_16x16x32_bf16 v[10:13], v[142:145], v[182:185], v[10:13]
	v_mfma_f32_16x16x32_bf16 v[6:9], v[134:137], v[178:181], v[6:9]
	v_mfma_f32_16x16x32_bf16 v[2:5], v[142:145], v[178:181], v[2:5]
.LBB0_907:
	s_and_b64 vcc, s[40:41], s[72:73]
	v_cndmask_b32_e64 v131, v209, 0, vcc
	v_cndmask_b32_e32 v130, v208, v198, vcc
	v_lshl_add_u64 v[234:235], s[70:71], 0, v[130:131]
	s_barrier
	v_add_u32_e32 v130, 0x18000, v224
	v_add_u32_e32 v142, 0x1c000, v224
	ds_read_b128 v[146:149], v130
	ds_read_b128 v[150:153], v130 offset:1024
	ds_read_b128 v[154:157], v130 offset:2048
	ds_read_b128 v[158:161], v130 offset:3072
	ds_read_b128 v[130:133], v142
	ds_read_b128 v[134:137], v142 offset:1024
	ds_read_b128 v[138:141], v142 offset:2048
	ds_read_b128 v[142:145], v142 offset:3072
	s_mov_b32 m0, s14
	v_lshl_add_u64 v[236:237], v[234:235], 0, v[194:195]
	s_waitcnt lgkmcnt(0)
	ds_read_b128 v[174:177], v228 offset:32768
	ds_read_b128 v[190:193], v228 offset:33792
	ds_read_b128 v[170:173], v228 offset:34816
	ds_read_b128 v[186:189], v228 offset:35840
	ds_read_b128 v[166:169], v228 offset:36864
	ds_read_b128 v[182:185], v228 offset:37888
	ds_read_b128 v[162:165], v228 offset:38912
	ds_read_b128 v[178:181], v228 offset:39936
	s_mov_b32 m0, s13
	s_nop 0
	global_load_lds_dwordx4 v196, s[98:99]
	s_mov_b32 m0, s14
	s_nop 0
	global_load_lds_dwordx4 v[236:237], off
	v_lshl_add_u64 v[234:235], v[234:235], 0, v[196:197]
	s_mov_b32 m0, s15
	s_nop 0
	global_load_lds_dwordx4 v[234:235], off
	s_waitcnt vmcnt(8) lgkmcnt(0)
	s_barrier
	v_mfma_f32_16x16x32_bf16 v[126:129], v[146:149], v[174:177], v[126:129]
	v_mfma_f32_16x16x32_bf16 v[122:125], v[154:157], v[174:177], v[122:125]
	v_mfma_f32_16x16x32_bf16 v[118:121], v[146:149], v[170:173], v[118:121]
	v_mfma_f32_16x16x32_bf16 v[114:117], v[154:157], v[170:173], v[114:117]
	v_mfma_f32_16x16x32_bf16 v[110:113], v[146:149], v[166:169], v[110:113]
	v_mfma_f32_16x16x32_bf16 v[106:109], v[154:157], v[166:169], v[106:109]
	v_mfma_f32_16x16x32_bf16 v[102:105], v[146:149], v[162:165], v[102:105]
	v_mfma_f32_16x16x32_bf16 v[98:101], v[154:157], v[162:165], v[98:101]
	v_mfma_f32_16x16x32_bf16 v[126:129], v[150:153], v[190:193], v[126:129]
	v_mfma_f32_16x16x32_bf16 v[122:125], v[158:161], v[190:193], v[122:125]
	v_mfma_f32_16x16x32_bf16 v[118:121], v[150:153], v[186:189], v[118:121]
	v_mfma_f32_16x16x32_bf16 v[114:117], v[158:161], v[186:189], v[114:117]
	v_mfma_f32_16x16x32_bf16 v[110:113], v[150:153], v[182:185], v[110:113]
	v_mfma_f32_16x16x32_bf16 v[106:109], v[158:161], v[182:185], v[106:109]
	v_mfma_f32_16x16x32_bf16 v[102:105], v[150:153], v[178:181], v[102:105]
	v_mfma_f32_16x16x32_bf16 v[98:101], v[158:161], v[178:181], v[98:101]
	v_mfma_f32_16x16x32_bf16 v[94:97], v[130:133], v[174:177], v[94:97]
	v_mfma_f32_16x16x32_bf16 v[90:93], v[138:141], v[174:177], v[90:93]
	v_mfma_f32_16x16x32_bf16 v[86:89], v[130:133], v[170:173], v[86:89]
	v_mfma_f32_16x16x32_bf16 v[82:85], v[138:141], v[170:173], v[82:85]
	v_mfma_f32_16x16x32_bf16 v[78:81], v[130:133], v[166:169], v[78:81]
	v_mfma_f32_16x16x32_bf16 v[74:77], v[138:141], v[166:169], v[74:77]
	v_mfma_f32_16x16x32_bf16 v[70:73], v[130:133], v[162:165], v[70:73]
	v_mfma_f32_16x16x32_bf16 v[66:69], v[138:141], v[162:165], v[66:69]
	v_mfma_f32_16x16x32_bf16 v[94:97], v[134:137], v[190:193], v[94:97]
	v_mfma_f32_16x16x32_bf16 v[90:93], v[142:145], v[190:193], v[90:93]
	v_mfma_f32_16x16x32_bf16 v[86:89], v[134:137], v[186:189], v[86:89]
	v_mfma_f32_16x16x32_bf16 v[82:85], v[142:145], v[186:189], v[82:85]
	v_mfma_f32_16x16x32_bf16 v[78:81], v[134:137], v[182:185], v[78:81]
	v_mfma_f32_16x16x32_bf16 v[74:77], v[142:145], v[182:185], v[74:77]
	v_mfma_f32_16x16x32_bf16 v[70:73], v[134:137], v[178:181], v[70:73]
	v_mfma_f32_16x16x32_bf16 v[66:69], v[142:145], v[178:181], v[66:69]
	s_barrier
	s_and_b64 vcc, exec, s[42:43]
	s_cbranch_vccnz .LBB0_909
	ds_read_b128 v[174:177], v228 offset:49152
	ds_read_b128 v[190:193], v228 offset:50176
	ds_read_b128 v[170:173], v228 offset:51200
	ds_read_b128 v[186:189], v228 offset:52224
	ds_read_b128 v[166:169], v228 offset:53248
	ds_read_b128 v[182:185], v228 offset:54272
	ds_read_b128 v[162:165], v228 offset:55296
	ds_read_b128 v[178:181], v228 offset:56320
.LBB0_909:
	s_add_u32 s72, s68, 0xe0000
	s_addc_u32 s73, s69, 0
	s_add_u32 s70, s70, 0x220000
	s_addc_u32 s71, s71, 0
	s_mov_b32 m0, s16
	s_add_u32 s68, s68, 0xe4000
	global_load_lds_dwordx4 v194, s[72:73]
	s_mov_b32 m0, s17
	s_addc_u32 s69, s69, 0
	global_load_lds_dwordx4 v196, s[72:73]
	s_mov_b32 m0, s54
	s_and_b64 vcc, exec, s[42:43]
	global_load_lds_dwordx4 v194, s[68:69]
	s_mov_b32 m0, s55
	s_nop 0
	global_load_lds_dwordx4 v196, s[68:69]
	s_mov_b32 m0, s23
	s_nop 0
	global_load_lds_dwordx4 v194, s[70:71]
	s_mov_b64 s[100:101], s[70:71]
	s_waitcnt vmcnt(7) lgkmcnt(0)
	s_barrier
	s_cbranch_vccnz .LBB0_902
	s_waitcnt lgkmcnt(0)
	v_mfma_f32_16x16x32_bf16 v[62:65], v[146:149], v[174:177], v[62:65]
	v_mfma_f32_16x16x32_bf16 v[58:61], v[154:157], v[174:177], v[58:61]
	v_mfma_f32_16x16x32_bf16 v[54:57], v[146:149], v[170:173], v[54:57]
	v_mfma_f32_16x16x32_bf16 v[50:53], v[154:157], v[170:173], v[50:53]
	v_mfma_f32_16x16x32_bf16 v[46:49], v[146:149], v[166:169], v[46:49]
	v_mfma_f32_16x16x32_bf16 v[42:45], v[154:157], v[166:169], v[42:45]
	v_mfma_f32_16x16x32_bf16 v[38:41], v[146:149], v[162:165], v[38:41]
	v_mfma_f32_16x16x32_bf16 v[34:37], v[154:157], v[162:165], v[34:37]
	v_mfma_f32_16x16x32_bf16 v[62:65], v[150:153], v[190:193], v[62:65]
	v_mfma_f32_16x16x32_bf16 v[58:61], v[158:161], v[190:193], v[58:61]
	v_mfma_f32_16x16x32_bf16 v[54:57], v[150:153], v[186:189], v[54:57]
	v_mfma_f32_16x16x32_bf16 v[50:53], v[158:161], v[186:189], v[50:53]
	v_mfma_f32_16x16x32_bf16 v[46:49], v[150:153], v[182:185], v[46:49]
	v_mfma_f32_16x16x32_bf16 v[42:45], v[158:161], v[182:185], v[42:45]
	v_mfma_f32_16x16x32_bf16 v[38:41], v[150:153], v[178:181], v[38:41]
	v_mfma_f32_16x16x32_bf16 v[34:37], v[158:161], v[178:181], v[34:37]
	v_mfma_f32_16x16x32_bf16 v[30:33], v[130:133], v[174:177], v[30:33]
	v_mfma_f32_16x16x32_bf16 v[26:29], v[138:141], v[174:177], v[26:29]
	v_mfma_f32_16x16x32_bf16 v[22:25], v[130:133], v[170:173], v[22:25]
	v_mfma_f32_16x16x32_bf16 v[18:21], v[138:141], v[170:173], v[18:21]
	v_mfma_f32_16x16x32_bf16 v[14:17], v[130:133], v[166:169], v[14:17]
	v_mfma_f32_16x16x32_bf16 v[10:13], v[138:141], v[166:169], v[10:13]
	v_mfma_f32_16x16x32_bf16 v[6:9], v[130:133], v[162:165], v[6:9]
	v_mfma_f32_16x16x32_bf16 v[2:5], v[138:141], v[162:165], v[2:5]
	v_mfma_f32_16x16x32_bf16 v[30:33], v[134:137], v[190:193], v[30:33]
	v_mfma_f32_16x16x32_bf16 v[26:29], v[142:145], v[190:193], v[26:29]
	v_mfma_f32_16x16x32_bf16 v[22:25], v[134:137], v[186:189], v[22:25]
	v_mfma_f32_16x16x32_bf16 v[18:21], v[142:145], v[186:189], v[18:21]
	v_mfma_f32_16x16x32_bf16 v[14:17], v[134:137], v[182:185], v[14:17]
	v_mfma_f32_16x16x32_bf16 v[10:13], v[142:145], v[182:185], v[10:13]
	v_mfma_f32_16x16x32_bf16 v[6:9], v[134:137], v[178:181], v[6:9]
	v_mfma_f32_16x16x32_bf16 v[2:5], v[142:145], v[178:181], v[2:5]
	s_branch .LBB0_902

.LBB0_1289:
	v_add_u32_e32 v142, 0x14000, v229
	ds_read_b128 v[146:149], v230
	ds_read_b128 v[150:153], v230 offset:1024
	ds_read_b128 v[154:157], v230 offset:2048
	ds_read_b128 v[158:161], v230 offset:3072
	ds_read_b128 v[130:133], v142
	ds_read_b128 v[134:137], v142 offset:1024
	ds_read_b128 v[138:141], v142 offset:2048
	ds_read_b128 v[142:145], v142 offset:3072
	v_lshl_add_u64 v[234:235], v[222:223], 0, s[48:49]
	s_add_i32 m0, s8, 0xc000
	s_waitcnt lgkmcnt(0)
	ds_read_b128 v[174:177], v231
	ds_read_b128 v[190:193], v231 offset:1024
	ds_read_b128 v[170:173], v231 offset:2048
	ds_read_b128 v[186:189], v231 offset:3072
	ds_read_b128 v[166:169], v231 offset:4096
	ds_read_b128 v[182:185], v231 offset:5120
	ds_read_b128 v[162:165], v231 offset:6144
	ds_read_b128 v[178:181], v231 offset:7168
	s_mov_b32 m0, s54
	s_nop 0
	global_load_lds_dwordx4 v196, s[100:101]
	s_add_i32 m0, s8, 0xc000
	s_nop 0
	global_load_lds_dwordx4 v[234:235], off
	v_lshl_add_u64 v[234:235], v[224:225], 0, s[48:49]
	s_add_i32 m0, s8, 0xe000
	s_nop 0
	global_load_lds_dwordx4 v[234:235], off
	s_waitcnt vmcnt(8) lgkmcnt(0)
	s_barrier
	v_mfma_f32_16x16x32_bf16 v[126:129], v[146:149], v[174:177], v[126:129]
	v_mfma_f32_16x16x32_bf16 v[122:125], v[154:157], v[174:177], v[122:125]
	v_mfma_f32_16x16x32_bf16 v[118:121], v[146:149], v[170:173], v[118:121]
	v_mfma_f32_16x16x32_bf16 v[110:113], v[154:157], v[170:173], v[110:113]
	v_mfma_f32_16x16x32_bf16 v[102:105], v[146:149], v[166:169], v[102:105]
	v_mfma_f32_16x16x32_bf16 v[94:97], v[154:157], v[166:169], v[94:97]
	v_mfma_f32_16x16x32_bf16 v[86:89], v[146:149], v[162:165], v[86:89]
	v_mfma_f32_16x16x32_bf16 v[78:81], v[154:157], v[162:165], v[78:81]
	v_mfma_f32_16x16x32_bf16 v[126:129], v[150:153], v[190:193], v[126:129]
	v_mfma_f32_16x16x32_bf16 v[122:125], v[158:161], v[190:193], v[122:125]
	v_mfma_f32_16x16x32_bf16 v[118:121], v[150:153], v[186:189], v[118:121]
	v_mfma_f32_16x16x32_bf16 v[110:113], v[158:161], v[186:189], v[110:113]
	v_mfma_f32_16x16x32_bf16 v[102:105], v[150:153], v[182:185], v[102:105]
	v_mfma_f32_16x16x32_bf16 v[94:97], v[158:161], v[182:185], v[94:97]
	v_mfma_f32_16x16x32_bf16 v[86:89], v[150:153], v[178:181], v[86:89]
	v_mfma_f32_16x16x32_bf16 v[78:81], v[158:161], v[178:181], v[78:81]
	v_mfma_f32_16x16x32_bf16 v[114:117], v[130:133], v[174:177], v[114:117]
	v_mfma_f32_16x16x32_bf16 v[106:109], v[138:141], v[174:177], v[106:109]
	v_mfma_f32_16x16x32_bf16 v[98:101], v[130:133], v[170:173], v[98:101]
	v_mfma_f32_16x16x32_bf16 v[90:93], v[138:141], v[170:173], v[90:93]
	v_mfma_f32_16x16x32_bf16 v[82:85], v[130:133], v[166:169], v[82:85]
	v_mfma_f32_16x16x32_bf16 v[74:77], v[138:141], v[166:169], v[74:77]
	v_mfma_f32_16x16x32_bf16 v[70:73], v[130:133], v[162:165], v[70:73]
	v_mfma_f32_16x16x32_bf16 v[66:69], v[138:141], v[162:165], v[66:69]
	v_mfma_f32_16x16x32_bf16 v[114:117], v[134:137], v[190:193], v[114:117]
	v_mfma_f32_16x16x32_bf16 v[106:109], v[142:145], v[190:193], v[106:109]
	v_mfma_f32_16x16x32_bf16 v[98:101], v[134:137], v[186:189], v[98:101]
	v_mfma_f32_16x16x32_bf16 v[90:93], v[142:145], v[186:189], v[90:93]
	v_mfma_f32_16x16x32_bf16 v[82:85], v[134:137], v[182:185], v[82:85]
	v_mfma_f32_16x16x32_bf16 v[74:77], v[142:145], v[182:185], v[74:77]
	v_mfma_f32_16x16x32_bf16 v[70:73], v[134:137], v[178:181], v[70:73]
	v_mfma_f32_16x16x32_bf16 v[66:69], v[142:145], v[178:181], v[66:69]
	s_barrier
	s_andn2_b64 s[42:43], exec, s[40:41]
	s_andn2_b64 vcc, exec, s[40:41]
	s_cbranch_vccnz .LBB0_1291
	ds_read_b128 v[174:177], v231 offset:16384
	ds_read_b128 v[190:193], v231 offset:17408
	ds_read_b128 v[170:173], v231 offset:18432
	ds_read_b128 v[186:189], v231 offset:19456
	ds_read_b128 v[166:169], v231 offset:20480
	ds_read_b128 v[182:185], v231 offset:21504
	ds_read_b128 v[162:165], v231 offset:22528
	ds_read_b128 v[178:181], v231 offset:23552
.LBB0_1291:
	s_add_u32 s52, s36, s48
	s_addc_u32 s53, s37, s49
	s_add_u32 s56, s52, 0x440000
	s_addc_u32 s57, s53, 0
	s_cmp_eq_u32 s48, 0x3fc0000
	s_cselect_b64 s[58:59], -1, 0
	s_and_b64 s[52:53], s[58:59], exec
	s_cselect_b32 s53, s31, s63
	s_cselect_b32 s52, s61, s62
	s_mov_b32 m0, s9
	s_cselect_b32 s57, s19, s57
	s_cselect_b32 s56, s29, s56
	s_add_u32 s68, s52, 0x4000
	global_load_lds_dwordx4 v194, s[52:53]
	s_mov_b32 m0, s10
	s_addc_u32 s69, s53, 0
	global_load_lds_dwordx4 v196, s[52:53]
	s_mov_b32 m0, s11
	s_and_b64 vcc, exec, s[42:43]
	global_load_lds_dwordx4 v194, s[68:69]
	s_mov_b32 m0, s12
	s_nop 0
	global_load_lds_dwordx4 v196, s[68:69]
	s_mov_b32 m0, s8
	s_nop 0
	global_load_lds_dwordx4 v194, s[56:57]
	s_mov_b64 s[98:99], s[56:57]
	s_waitcnt vmcnt(7) lgkmcnt(0)
	s_barrier
	s_cbranch_vccnz .LBB0_1293
	s_waitcnt lgkmcnt(0)
	v_mfma_f32_16x16x32_bf16 v[62:65], v[146:149], v[174:177], v[62:65]
	v_mfma_f32_16x16x32_bf16 v[58:61], v[154:157], v[174:177], v[58:61]
	v_mfma_f32_16x16x32_bf16 v[46:49], v[146:149], v[170:173], v[46:49]
	v_mfma_f32_16x16x32_bf16 v[42:45], v[154:157], v[170:173], v[42:45]
	v_mfma_f32_16x16x32_bf16 v[30:33], v[146:149], v[166:169], v[30:33]
	v_mfma_f32_16x16x32_bf16 v[26:29], v[154:157], v[166:169], v[26:29]
	v_mfma_f32_16x16x32_bf16 v[14:17], v[146:149], v[162:165], v[14:17]
	v_mfma_f32_16x16x32_bf16 v[10:13], v[154:157], v[162:165], v[10:13]
	v_mfma_f32_16x16x32_bf16 v[62:65], v[150:153], v[190:193], v[62:65]
	v_mfma_f32_16x16x32_bf16 v[58:61], v[158:161], v[190:193], v[58:61]
	v_mfma_f32_16x16x32_bf16 v[46:49], v[150:153], v[186:189], v[46:49]
	v_mfma_f32_16x16x32_bf16 v[42:45], v[158:161], v[186:189], v[42:45]
	v_mfma_f32_16x16x32_bf16 v[30:33], v[150:153], v[182:185], v[30:33]
	v_mfma_f32_16x16x32_bf16 v[26:29], v[158:161], v[182:185], v[26:29]
	v_mfma_f32_16x16x32_bf16 v[14:17], v[150:153], v[178:181], v[14:17]
	v_mfma_f32_16x16x32_bf16 v[10:13], v[158:161], v[178:181], v[10:13]
	v_mfma_f32_16x16x32_bf16 v[54:57], v[130:133], v[174:177], v[54:57]
	v_mfma_f32_16x16x32_bf16 v[50:53], v[138:141], v[174:177], v[50:53]
	v_mfma_f32_16x16x32_bf16 v[38:41], v[130:133], v[170:173], v[38:41]
	v_mfma_f32_16x16x32_bf16 v[34:37], v[138:141], v[170:173], v[34:37]
	v_mfma_f32_16x16x32_bf16 v[22:25], v[130:133], v[166:169], v[22:25]
	v_mfma_f32_16x16x32_bf16 v[18:21], v[138:141], v[166:169], v[18:21]
	v_mfma_f32_16x16x32_bf16 v[6:9], v[130:133], v[162:165], v[6:9]
	v_mfma_f32_16x16x32_bf16 v[2:5], v[138:141], v[162:165], v[2:5]
	v_mfma_f32_16x16x32_bf16 v[54:57], v[134:137], v[190:193], v[54:57]
	v_mfma_f32_16x16x32_bf16 v[50:53], v[142:145], v[190:193], v[50:53]
	v_mfma_f32_16x16x32_bf16 v[38:41], v[134:137], v[186:189], v[38:41]
	v_mfma_f32_16x16x32_bf16 v[34:37], v[142:145], v[186:189], v[34:37]
	v_mfma_f32_16x16x32_bf16 v[22:25], v[134:137], v[182:185], v[22:25]
	v_mfma_f32_16x16x32_bf16 v[18:21], v[142:145], v[182:185], v[18:21]
	v_mfma_f32_16x16x32_bf16 v[6:9], v[134:137], v[178:181], v[6:9]
	v_mfma_f32_16x16x32_bf16 v[2:5], v[142:145], v[178:181], v[2:5]
.LBB0_1293:
	s_and_b64 vcc, s[34:35], s[58:59]
	v_cndmask_b32_e64 v131, v221, 0, vcc
	v_cndmask_b32_e32 v130, v220, v198, vcc
	v_lshl_add_u64 v[234:235], s[56:57], 0, v[130:131]
	s_barrier
	v_add_u32_e32 v130, 0x18000, v229
	v_add_u32_e32 v142, 0x1c000, v229
	ds_read_b128 v[146:149], v130
	ds_read_b128 v[150:153], v130 offset:1024
	ds_read_b128 v[154:157], v130 offset:2048
	ds_read_b128 v[158:161], v130 offset:3072
	ds_read_b128 v[130:133], v142
	ds_read_b128 v[134:137], v142 offset:1024
	ds_read_b128 v[138:141], v142 offset:2048
	ds_read_b128 v[142:145], v142 offset:3072
	s_mov_b32 m0, s14
	v_lshl_add_u64 v[236:237], v[234:235], 0, v[194:195]
	s_waitcnt lgkmcnt(0)
	ds_read_b128 v[174:177], v231 offset:32768
	ds_read_b128 v[190:193], v231 offset:33792
	ds_read_b128 v[170:173], v231 offset:34816
	ds_read_b128 v[186:189], v231 offset:35840
	ds_read_b128 v[166:169], v231 offset:36864
	ds_read_b128 v[182:185], v231 offset:37888
	ds_read_b128 v[162:165], v231 offset:38912
	ds_read_b128 v[178:181], v231 offset:39936
	s_mov_b32 m0, s13
	s_nop 0
	global_load_lds_dwordx4 v196, s[98:99]
	s_mov_b32 m0, s14
	s_nop 0
	global_load_lds_dwordx4 v[236:237], off
	v_lshl_add_u64 v[234:235], v[234:235], 0, v[196:197]
	s_mov_b32 m0, s15
	s_nop 0
	global_load_lds_dwordx4 v[234:235], off
	s_waitcnt vmcnt(8) lgkmcnt(0)
	s_barrier
	v_mfma_f32_16x16x32_bf16 v[126:129], v[146:149], v[174:177], v[126:129]
	v_mfma_f32_16x16x32_bf16 v[122:125], v[154:157], v[174:177], v[122:125]
	v_mfma_f32_16x16x32_bf16 v[118:121], v[146:149], v[170:173], v[118:121]
	v_mfma_f32_16x16x32_bf16 v[110:113], v[154:157], v[170:173], v[110:113]
	v_mfma_f32_16x16x32_bf16 v[102:105], v[146:149], v[166:169], v[102:105]
	v_mfma_f32_16x16x32_bf16 v[94:97], v[154:157], v[166:169], v[94:97]
	v_mfma_f32_16x16x32_bf16 v[86:89], v[146:149], v[162:165], v[86:89]
	v_mfma_f32_16x16x32_bf16 v[78:81], v[154:157], v[162:165], v[78:81]
	v_mfma_f32_16x16x32_bf16 v[126:129], v[150:153], v[190:193], v[126:129]
	v_mfma_f32_16x16x32_bf16 v[122:125], v[158:161], v[190:193], v[122:125]
	v_mfma_f32_16x16x32_bf16 v[118:121], v[150:153], v[186:189], v[118:121]
	v_mfma_f32_16x16x32_bf16 v[110:113], v[158:161], v[186:189], v[110:113]
	v_mfma_f32_16x16x32_bf16 v[102:105], v[150:153], v[182:185], v[102:105]
	v_mfma_f32_16x16x32_bf16 v[94:97], v[158:161], v[182:185], v[94:97]
	v_mfma_f32_16x16x32_bf16 v[86:89], v[150:153], v[178:181], v[86:89]
	v_mfma_f32_16x16x32_bf16 v[78:81], v[158:161], v[178:181], v[78:81]
	v_mfma_f32_16x16x32_bf16 v[114:117], v[130:133], v[174:177], v[114:117]
	v_mfma_f32_16x16x32_bf16 v[106:109], v[138:141], v[174:177], v[106:109]
	v_mfma_f32_16x16x32_bf16 v[98:101], v[130:133], v[170:173], v[98:101]
	v_mfma_f32_16x16x32_bf16 v[90:93], v[138:141], v[170:173], v[90:93]
	v_mfma_f32_16x16x32_bf16 v[82:85], v[130:133], v[166:169], v[82:85]
	v_mfma_f32_16x16x32_bf16 v[74:77], v[138:141], v[166:169], v[74:77]
	v_mfma_f32_16x16x32_bf16 v[70:73], v[130:133], v[162:165], v[70:73]
	v_mfma_f32_16x16x32_bf16 v[66:69], v[138:141], v[162:165], v[66:69]
	v_mfma_f32_16x16x32_bf16 v[114:117], v[134:137], v[190:193], v[114:117]
	v_mfma_f32_16x16x32_bf16 v[106:109], v[142:145], v[190:193], v[106:109]
	v_mfma_f32_16x16x32_bf16 v[98:101], v[134:137], v[186:189], v[98:101]
	v_mfma_f32_16x16x32_bf16 v[90:93], v[142:145], v[186:189], v[90:93]
	v_mfma_f32_16x16x32_bf16 v[82:85], v[134:137], v[182:185], v[82:85]
	v_mfma_f32_16x16x32_bf16 v[74:77], v[142:145], v[182:185], v[74:77]
	v_mfma_f32_16x16x32_bf16 v[70:73], v[134:137], v[178:181], v[70:73]
	v_mfma_f32_16x16x32_bf16 v[66:69], v[142:145], v[178:181], v[66:69]
	s_barrier
	s_and_b64 vcc, exec, s[42:43]
	s_cbranch_vccnz .LBB0_1295
	ds_read_b128 v[174:177], v231 offset:49152
	ds_read_b128 v[190:193], v231 offset:50176
	ds_read_b128 v[170:173], v231 offset:51200
	ds_read_b128 v[186:189], v231 offset:52224
	ds_read_b128 v[166:169], v231 offset:53248
	ds_read_b128 v[182:185], v231 offset:54272
	ds_read_b128 v[162:165], v231 offset:55296
	ds_read_b128 v[178:181], v231 offset:56320
.LBB0_1295:
	s_add_u32 s58, s52, 0x40000
	s_addc_u32 s59, s53, 0
	s_add_u32 s56, s56, 0x220000
	s_addc_u32 s57, s57, 0
	s_mov_b32 m0, s16
	s_add_u32 s52, s52, 0x44000
	global_load_lds_dwordx4 v194, s[58:59]
	s_mov_b32 m0, s17
	s_addc_u32 s53, s53, 0
	global_load_lds_dwordx4 v196, s[58:59]
	s_mov_b32 m0, s55
	s_and_b64 vcc, exec, s[42:43]
	global_load_lds_dwordx4 v194, s[52:53]
	s_mov_b32 m0, s60
	s_nop 0
	global_load_lds_dwordx4 v196, s[52:53]
	s_mov_b32 m0, s27
	s_nop 0
	global_load_lds_dwordx4 v194, s[56:57]
	s_mov_b64 s[100:101], s[56:57]
	s_waitcnt vmcnt(7) lgkmcnt(0)
	s_barrier
	s_cbranch_vccnz .LBB0_1288
	s_waitcnt lgkmcnt(0)
	v_mfma_f32_16x16x32_bf16 v[62:65], v[146:149], v[174:177], v[62:65]
	v_mfma_f32_16x16x32_bf16 v[58:61], v[154:157], v[174:177], v[58:61]
	v_mfma_f32_16x16x32_bf16 v[46:49], v[146:149], v[170:173], v[46:49]
	v_mfma_f32_16x16x32_bf16 v[42:45], v[154:157], v[170:173], v[42:45]
	v_mfma_f32_16x16x32_bf16 v[30:33], v[146:149], v[166:169], v[30:33]
	v_mfma_f32_16x16x32_bf16 v[26:29], v[154:157], v[166:169], v[26:29]
	v_mfma_f32_16x16x32_bf16 v[14:17], v[146:149], v[162:165], v[14:17]
	v_mfma_f32_16x16x32_bf16 v[10:13], v[154:157], v[162:165], v[10:13]
	v_mfma_f32_16x16x32_bf16 v[62:65], v[150:153], v[190:193], v[62:65]
	v_mfma_f32_16x16x32_bf16 v[58:61], v[158:161], v[190:193], v[58:61]
	v_mfma_f32_16x16x32_bf16 v[46:49], v[150:153], v[186:189], v[46:49]
	v_mfma_f32_16x16x32_bf16 v[42:45], v[158:161], v[186:189], v[42:45]
	v_mfma_f32_16x16x32_bf16 v[30:33], v[150:153], v[182:185], v[30:33]
	v_mfma_f32_16x16x32_bf16 v[26:29], v[158:161], v[182:185], v[26:29]
	v_mfma_f32_16x16x32_bf16 v[14:17], v[150:153], v[178:181], v[14:17]
	v_mfma_f32_16x16x32_bf16 v[10:13], v[158:161], v[178:181], v[10:13]
	v_mfma_f32_16x16x32_bf16 v[54:57], v[130:133], v[174:177], v[54:57]
	v_mfma_f32_16x16x32_bf16 v[50:53], v[138:141], v[174:177], v[50:53]
	v_mfma_f32_16x16x32_bf16 v[38:41], v[130:133], v[170:173], v[38:41]
	v_mfma_f32_16x16x32_bf16 v[34:37], v[138:141], v[170:173], v[34:37]
	v_mfma_f32_16x16x32_bf16 v[22:25], v[130:133], v[166:169], v[22:25]
	v_mfma_f32_16x16x32_bf16 v[18:21], v[138:141], v[166:169], v[18:21]
	v_mfma_f32_16x16x32_bf16 v[6:9], v[130:133], v[162:165], v[6:9]
	v_mfma_f32_16x16x32_bf16 v[2:5], v[138:141], v[162:165], v[2:5]
	v_mfma_f32_16x16x32_bf16 v[54:57], v[134:137], v[190:193], v[54:57]
	v_mfma_f32_16x16x32_bf16 v[50:53], v[142:145], v[190:193], v[50:53]
	v_mfma_f32_16x16x32_bf16 v[38:41], v[134:137], v[186:189], v[38:41]
	v_mfma_f32_16x16x32_bf16 v[34:37], v[142:145], v[186:189], v[34:37]
	v_mfma_f32_16x16x32_bf16 v[22:25], v[134:137], v[182:185], v[22:25]
	v_mfma_f32_16x16x32_bf16 v[18:21], v[142:145], v[182:185], v[18:21]
	v_mfma_f32_16x16x32_bf16 v[6:9], v[134:137], v[178:181], v[6:9]
	v_mfma_f32_16x16x32_bf16 v[2:5], v[142:145], v[178:181], v[2:5]
	s_branch .LBB0_1288

.LBB0_1612:
	v_add_u32_e32 v1, 0x10000, v232
	ds_read_b128 v[146:149], v1
	ds_read_b128 v[150:153], v1 offset:1024
	ds_read_b128 v[154:157], v1 offset:2048
	ds_read_b128 v[158:161], v1 offset:3072
	v_add_u32_e32 v1, 0x14000, v232
	ds_read_b128 v[130:133], v1
	ds_read_b128 v[134:137], v1 offset:1024
	ds_read_b128 v[138:141], v1 offset:2048
	ds_read_b128 v[142:145], v1 offset:3072
	v_lshl_add_u64 v[236:237], v[226:227], 0, s[48:49]
	s_add_i32 m0, s9, 0xc000
	s_waitcnt lgkmcnt(0)
	ds_read_b128 v[174:177], v233
	ds_read_b128 v[190:193], v233 offset:1024
	ds_read_b128 v[170:173], v233 offset:2048
	ds_read_b128 v[186:189], v233 offset:3072
	ds_read_b128 v[166:169], v233 offset:4096
	ds_read_b128 v[182:185], v233 offset:5120
	ds_read_b128 v[162:165], v233 offset:6144
	ds_read_b128 v[178:181], v233 offset:7168
	s_mov_b32 m0, s55
	s_nop 0
	global_load_lds_dwordx4 v196, s[100:101]
	s_add_i32 m0, s9, 0xc000
	s_nop 0
	global_load_lds_dwordx4 v[236:237], off
	v_lshl_add_u64 v[236:237], v[228:229], 0, s[48:49]
	s_add_i32 m0, s9, 0xe000
	s_nop 0
	global_load_lds_dwordx4 v[236:237], off
	s_waitcnt vmcnt(8) lgkmcnt(0)
	s_barrier
	v_mfma_f32_16x16x32_bf16 v[126:129], v[146:149], v[174:177], v[126:129]
	v_mfma_f32_16x16x32_bf16 v[122:125], v[154:157], v[174:177], v[122:125]
	v_mfma_f32_16x16x32_bf16 v[118:121], v[146:149], v[170:173], v[118:121]
	v_mfma_f32_16x16x32_bf16 v[110:113], v[154:157], v[170:173], v[110:113]
	v_mfma_f32_16x16x32_bf16 v[102:105], v[146:149], v[166:169], v[102:105]
	v_mfma_f32_16x16x32_bf16 v[94:97], v[154:157], v[166:169], v[94:97]
	v_mfma_f32_16x16x32_bf16 v[86:89], v[146:149], v[162:165], v[86:89]
	v_mfma_f32_16x16x32_bf16 v[78:81], v[154:157], v[162:165], v[78:81]
	v_mfma_f32_16x16x32_bf16 v[126:129], v[150:153], v[190:193], v[126:129]
	v_mfma_f32_16x16x32_bf16 v[122:125], v[158:161], v[190:193], v[122:125]
	v_mfma_f32_16x16x32_bf16 v[118:121], v[150:153], v[186:189], v[118:121]
	v_mfma_f32_16x16x32_bf16 v[110:113], v[158:161], v[186:189], v[110:113]
	v_mfma_f32_16x16x32_bf16 v[102:105], v[150:153], v[182:185], v[102:105]
	v_mfma_f32_16x16x32_bf16 v[94:97], v[158:161], v[182:185], v[94:97]
	v_mfma_f32_16x16x32_bf16 v[86:89], v[150:153], v[178:181], v[86:89]
	v_mfma_f32_16x16x32_bf16 v[78:81], v[158:161], v[178:181], v[78:81]
	v_mfma_f32_16x16x32_bf16 v[114:117], v[130:133], v[174:177], v[114:117]
	v_mfma_f32_16x16x32_bf16 v[106:109], v[138:141], v[174:177], v[106:109]
	v_mfma_f32_16x16x32_bf16 v[98:101], v[130:133], v[170:173], v[98:101]
	v_mfma_f32_16x16x32_bf16 v[90:93], v[138:141], v[170:173], v[90:93]
	v_mfma_f32_16x16x32_bf16 v[82:85], v[130:133], v[166:169], v[82:85]
	v_mfma_f32_16x16x32_bf16 v[74:77], v[138:141], v[166:169], v[74:77]
	v_mfma_f32_16x16x32_bf16 v[70:73], v[130:133], v[162:165], v[70:73]
	v_mfma_f32_16x16x32_bf16 v[66:69], v[138:141], v[162:165], v[66:69]
	v_mfma_f32_16x16x32_bf16 v[114:117], v[134:137], v[190:193], v[114:117]
	v_mfma_f32_16x16x32_bf16 v[106:109], v[142:145], v[190:193], v[106:109]
	v_mfma_f32_16x16x32_bf16 v[98:101], v[134:137], v[186:189], v[98:101]
	v_mfma_f32_16x16x32_bf16 v[90:93], v[142:145], v[186:189], v[90:93]
	v_mfma_f32_16x16x32_bf16 v[82:85], v[134:137], v[182:185], v[82:85]
	v_mfma_f32_16x16x32_bf16 v[74:77], v[142:145], v[182:185], v[74:77]
	v_mfma_f32_16x16x32_bf16 v[70:73], v[134:137], v[178:181], v[70:73]
	v_mfma_f32_16x16x32_bf16 v[66:69], v[142:145], v[178:181], v[66:69]
	s_barrier
	s_andn2_b64 s[42:43], exec, s[40:41]
	s_andn2_b64 vcc, exec, s[40:41]
	s_cbranch_vccnz .LBB0_1614
	ds_read_b128 v[174:177], v233 offset:16384
	ds_read_b128 v[190:193], v233 offset:17408
	ds_read_b128 v[170:173], v233 offset:18432
	ds_read_b128 v[186:189], v233 offset:19456
	ds_read_b128 v[166:169], v233 offset:20480
	ds_read_b128 v[182:185], v233 offset:21504
	ds_read_b128 v[162:165], v233 offset:22528
	ds_read_b128 v[178:181], v233 offset:23552
.LBB0_1614:
	s_add_u32 s50, s46, s48
	s_addc_u32 s51, s47, s49
	s_add_u32 s52, s50, 0x440000
	s_addc_u32 s53, s51, 0
	s_cmp_eq_u32 s48, 0x3fc0000
	s_cselect_b64 s[56:57], -1, 0
	s_and_b64 s[50:51], s[56:57], exec
	s_cselect_b32 s51, s31, s61
	s_cselect_b32 s50, s35, s60
	s_mov_b32 m0, s10
	s_cselect_b32 s53, s19, s53
	s_cselect_b32 s52, s20, s52
	s_add_u32 s68, s50, 0x4000
	global_load_lds_dwordx4 v194, s[50:51]
	s_mov_b32 m0, s11
	s_addc_u32 s69, s51, 0
	global_load_lds_dwordx4 v196, s[50:51]
	s_mov_b32 m0, s12
	s_and_b64 vcc, exec, s[42:43]
	global_load_lds_dwordx4 v194, s[68:69]
	s_mov_b32 m0, s13
	s_nop 0
	global_load_lds_dwordx4 v196, s[68:69]
	s_mov_b32 m0, s9
	s_nop 0
	global_load_lds_dwordx4 v194, s[52:53]
	s_mov_b64 s[98:99], s[52:53]
	s_waitcnt vmcnt(7) lgkmcnt(0)
	s_barrier
	s_cbranch_vccnz .LBB0_1616
	s_waitcnt lgkmcnt(0)
	v_mfma_f32_16x16x32_bf16 v[62:65], v[146:149], v[174:177], v[62:65]
	v_mfma_f32_16x16x32_bf16 v[58:61], v[154:157], v[174:177], v[58:61]
	v_mfma_f32_16x16x32_bf16 v[46:49], v[146:149], v[170:173], v[46:49]
	v_mfma_f32_16x16x32_bf16 v[42:45], v[154:157], v[170:173], v[42:45]
	v_mfma_f32_16x16x32_bf16 v[30:33], v[146:149], v[166:169], v[30:33]
	v_mfma_f32_16x16x32_bf16 v[26:29], v[154:157], v[166:169], v[26:29]
	v_mfma_f32_16x16x32_bf16 v[14:17], v[146:149], v[162:165], v[14:17]
	v_mfma_f32_16x16x32_bf16 v[10:13], v[154:157], v[162:165], v[10:13]
	v_mfma_f32_16x16x32_bf16 v[62:65], v[150:153], v[190:193], v[62:65]
	v_mfma_f32_16x16x32_bf16 v[58:61], v[158:161], v[190:193], v[58:61]
	v_mfma_f32_16x16x32_bf16 v[46:49], v[150:153], v[186:189], v[46:49]
	v_mfma_f32_16x16x32_bf16 v[42:45], v[158:161], v[186:189], v[42:45]
	v_mfma_f32_16x16x32_bf16 v[30:33], v[150:153], v[182:185], v[30:33]
	v_mfma_f32_16x16x32_bf16 v[26:29], v[158:161], v[182:185], v[26:29]
	v_mfma_f32_16x16x32_bf16 v[14:17], v[150:153], v[178:181], v[14:17]
	v_mfma_f32_16x16x32_bf16 v[10:13], v[158:161], v[178:181], v[10:13]
	v_mfma_f32_16x16x32_bf16 v[54:57], v[130:133], v[174:177], v[54:57]
	v_mfma_f32_16x16x32_bf16 v[50:53], v[138:141], v[174:177], v[50:53]
	v_mfma_f32_16x16x32_bf16 v[38:41], v[130:133], v[170:173], v[38:41]
	v_mfma_f32_16x16x32_bf16 v[34:37], v[138:141], v[170:173], v[34:37]
	v_mfma_f32_16x16x32_bf16 v[22:25], v[130:133], v[166:169], v[22:25]
	v_mfma_f32_16x16x32_bf16 v[18:21], v[138:141], v[166:169], v[18:21]
	v_mfma_f32_16x16x32_bf16 v[6:9], v[130:133], v[162:165], v[6:9]
	v_mfma_f32_16x16x32_bf16 v[2:5], v[138:141], v[162:165], v[2:5]
	v_mfma_f32_16x16x32_bf16 v[54:57], v[134:137], v[190:193], v[54:57]
	v_mfma_f32_16x16x32_bf16 v[50:53], v[142:145], v[190:193], v[50:53]
	v_mfma_f32_16x16x32_bf16 v[38:41], v[134:137], v[186:189], v[38:41]
	v_mfma_f32_16x16x32_bf16 v[34:37], v[142:145], v[186:189], v[34:37]
	v_mfma_f32_16x16x32_bf16 v[22:25], v[134:137], v[182:185], v[22:25]
	v_mfma_f32_16x16x32_bf16 v[18:21], v[142:145], v[182:185], v[18:21]
	v_mfma_f32_16x16x32_bf16 v[6:9], v[134:137], v[178:181], v[6:9]
	v_mfma_f32_16x16x32_bf16 v[2:5], v[142:145], v[178:181], v[2:5]
.LBB0_1616:
	s_and_b64 vcc, s[38:39], s[56:57]
	v_cndmask_b32_e64 v131, v225, 0, vcc
	v_cndmask_b32_e32 v130, v224, v198, vcc
	v_lshl_add_u64 v[236:237], s[52:53], 0, v[130:131]
	s_barrier
	v_add_u32_e32 v1, 0x18000, v232
	ds_read_b128 v[146:149], v1
	ds_read_b128 v[150:153], v1 offset:1024
	ds_read_b128 v[154:157], v1 offset:2048
	ds_read_b128 v[158:161], v1 offset:3072
	v_add_u32_e32 v1, 0x1c000, v232
	ds_read_b128 v[130:133], v1
	ds_read_b128 v[134:137], v1 offset:1024
	ds_read_b128 v[138:141], v1 offset:2048
	ds_read_b128 v[142:145], v1 offset:3072
	s_mov_b32 m0, s15
	v_lshl_add_u64 v[238:239], v[236:237], 0, v[194:195]
	s_waitcnt lgkmcnt(0)
	ds_read_b128 v[174:177], v233 offset:32768
	ds_read_b128 v[190:193], v233 offset:33792
	ds_read_b128 v[170:173], v233 offset:34816
	ds_read_b128 v[186:189], v233 offset:35840
	ds_read_b128 v[166:169], v233 offset:36864
	ds_read_b128 v[182:185], v233 offset:37888
	ds_read_b128 v[162:165], v233 offset:38912
	ds_read_b128 v[178:181], v233 offset:39936
	s_mov_b32 m0, s14
	s_nop 0
	global_load_lds_dwordx4 v196, s[98:99]
	s_mov_b32 m0, s15
	s_nop 0
	global_load_lds_dwordx4 v[238:239], off
	v_lshl_add_u64 v[236:237], v[236:237], 0, v[196:197]
	s_mov_b32 m0, s16
	s_nop 0
	global_load_lds_dwordx4 v[236:237], off
	s_waitcnt vmcnt(8) lgkmcnt(0)
	s_barrier
	v_mfma_f32_16x16x32_bf16 v[126:129], v[146:149], v[174:177], v[126:129]
	v_mfma_f32_16x16x32_bf16 v[122:125], v[154:157], v[174:177], v[122:125]
	v_mfma_f32_16x16x32_bf16 v[118:121], v[146:149], v[170:173], v[118:121]
	v_mfma_f32_16x16x32_bf16 v[110:113], v[154:157], v[170:173], v[110:113]
	v_mfma_f32_16x16x32_bf16 v[102:105], v[146:149], v[166:169], v[102:105]
	v_mfma_f32_16x16x32_bf16 v[94:97], v[154:157], v[166:169], v[94:97]
	v_mfma_f32_16x16x32_bf16 v[86:89], v[146:149], v[162:165], v[86:89]
	v_mfma_f32_16x16x32_bf16 v[78:81], v[154:157], v[162:165], v[78:81]
	v_mfma_f32_16x16x32_bf16 v[126:129], v[150:153], v[190:193], v[126:129]
	v_mfma_f32_16x16x32_bf16 v[122:125], v[158:161], v[190:193], v[122:125]
	v_mfma_f32_16x16x32_bf16 v[118:121], v[150:153], v[186:189], v[118:121]
	v_mfma_f32_16x16x32_bf16 v[110:113], v[158:161], v[186:189], v[110:113]
	v_mfma_f32_16x16x32_bf16 v[102:105], v[150:153], v[182:185], v[102:105]
	v_mfma_f32_16x16x32_bf16 v[94:97], v[158:161], v[182:185], v[94:97]
	v_mfma_f32_16x16x32_bf16 v[86:89], v[150:153], v[178:181], v[86:89]
	v_mfma_f32_16x16x32_bf16 v[78:81], v[158:161], v[178:181], v[78:81]
	v_mfma_f32_16x16x32_bf16 v[114:117], v[130:133], v[174:177], v[114:117]
	v_mfma_f32_16x16x32_bf16 v[106:109], v[138:141], v[174:177], v[106:109]
	v_mfma_f32_16x16x32_bf16 v[98:101], v[130:133], v[170:173], v[98:101]
	v_mfma_f32_16x16x32_bf16 v[90:93], v[138:141], v[170:173], v[90:93]
	v_mfma_f32_16x16x32_bf16 v[82:85], v[130:133], v[166:169], v[82:85]
	v_mfma_f32_16x16x32_bf16 v[74:77], v[138:141], v[166:169], v[74:77]
	v_mfma_f32_16x16x32_bf16 v[70:73], v[130:133], v[162:165], v[70:73]
	v_mfma_f32_16x16x32_bf16 v[66:69], v[138:141], v[162:165], v[66:69]
	v_mfma_f32_16x16x32_bf16 v[114:117], v[134:137], v[190:193], v[114:117]
	v_mfma_f32_16x16x32_bf16 v[106:109], v[142:145], v[190:193], v[106:109]
	v_mfma_f32_16x16x32_bf16 v[98:101], v[134:137], v[186:189], v[98:101]
	v_mfma_f32_16x16x32_bf16 v[90:93], v[142:145], v[186:189], v[90:93]
	v_mfma_f32_16x16x32_bf16 v[82:85], v[134:137], v[182:185], v[82:85]
	v_mfma_f32_16x16x32_bf16 v[74:77], v[142:145], v[182:185], v[74:77]
	v_mfma_f32_16x16x32_bf16 v[70:73], v[134:137], v[178:181], v[70:73]
	v_mfma_f32_16x16x32_bf16 v[66:69], v[142:145], v[178:181], v[66:69]
	s_barrier
	s_and_b64 vcc, exec, s[42:43]
	s_cbranch_vccnz .LBB0_1618
	ds_read_b128 v[174:177], v233 offset:49152
	ds_read_b128 v[190:193], v233 offset:50176
	ds_read_b128 v[170:173], v233 offset:51200
	ds_read_b128 v[186:189], v233 offset:52224
	ds_read_b128 v[166:169], v233 offset:53248
	ds_read_b128 v[182:185], v233 offset:54272
	ds_read_b128 v[162:165], v233 offset:55296
	ds_read_b128 v[178:181], v233 offset:56320
.LBB0_1618:
	s_add_u32 s56, s50, 0x40000
	s_addc_u32 s57, s51, 0
	s_add_u32 s52, s52, 0x220000
	s_addc_u32 s53, s53, 0
	s_mov_b32 m0, s17
	s_add_u32 s50, s50, 0x44000
	global_load_lds_dwordx4 v194, s[56:57]
	s_mov_b32 m0, s29
	s_addc_u32 s51, s51, 0
	global_load_lds_dwordx4 v196, s[56:57]
	s_mov_b32 m0, s58
	s_and_b64 vcc, exec, s[42:43]
	global_load_lds_dwordx4 v194, s[50:51]
	s_mov_b32 m0, s59
	s_nop 0
	global_load_lds_dwordx4 v196, s[50:51]
	s_mov_b32 m0, s54
	s_nop 0
	global_load_lds_dwordx4 v194, s[52:53]
	s_mov_b64 s[100:101], s[52:53]
	s_waitcnt vmcnt(7) lgkmcnt(0)
	s_barrier
	s_cbranch_vccnz .LBB0_1611
	s_waitcnt lgkmcnt(0)
	v_mfma_f32_16x16x32_bf16 v[62:65], v[146:149], v[174:177], v[62:65]
	v_mfma_f32_16x16x32_bf16 v[58:61], v[154:157], v[174:177], v[58:61]
	v_mfma_f32_16x16x32_bf16 v[46:49], v[146:149], v[170:173], v[46:49]
	v_mfma_f32_16x16x32_bf16 v[42:45], v[154:157], v[170:173], v[42:45]
	v_mfma_f32_16x16x32_bf16 v[30:33], v[146:149], v[166:169], v[30:33]
	v_mfma_f32_16x16x32_bf16 v[26:29], v[154:157], v[166:169], v[26:29]
	v_mfma_f32_16x16x32_bf16 v[14:17], v[146:149], v[162:165], v[14:17]
	v_mfma_f32_16x16x32_bf16 v[10:13], v[154:157], v[162:165], v[10:13]
	v_mfma_f32_16x16x32_bf16 v[62:65], v[150:153], v[190:193], v[62:65]
	v_mfma_f32_16x16x32_bf16 v[58:61], v[158:161], v[190:193], v[58:61]
	v_mfma_f32_16x16x32_bf16 v[46:49], v[150:153], v[186:189], v[46:49]
	v_mfma_f32_16x16x32_bf16 v[42:45], v[158:161], v[186:189], v[42:45]
	v_mfma_f32_16x16x32_bf16 v[30:33], v[150:153], v[182:185], v[30:33]
	v_mfma_f32_16x16x32_bf16 v[26:29], v[158:161], v[182:185], v[26:29]
	v_mfma_f32_16x16x32_bf16 v[14:17], v[150:153], v[178:181], v[14:17]
	v_mfma_f32_16x16x32_bf16 v[10:13], v[158:161], v[178:181], v[10:13]
	v_mfma_f32_16x16x32_bf16 v[54:57], v[130:133], v[174:177], v[54:57]
	v_mfma_f32_16x16x32_bf16 v[50:53], v[138:141], v[174:177], v[50:53]
	v_mfma_f32_16x16x32_bf16 v[38:41], v[130:133], v[170:173], v[38:41]
	v_mfma_f32_16x16x32_bf16 v[34:37], v[138:141], v[170:173], v[34:37]
	v_mfma_f32_16x16x32_bf16 v[22:25], v[130:133], v[166:169], v[22:25]
	v_mfma_f32_16x16x32_bf16 v[18:21], v[138:141], v[166:169], v[18:21]
	v_mfma_f32_16x16x32_bf16 v[6:9], v[130:133], v[162:165], v[6:9]
	v_mfma_f32_16x16x32_bf16 v[2:5], v[138:141], v[162:165], v[2:5]
	v_mfma_f32_16x16x32_bf16 v[54:57], v[134:137], v[190:193], v[54:57]
	v_mfma_f32_16x16x32_bf16 v[50:53], v[142:145], v[190:193], v[50:53]
	v_mfma_f32_16x16x32_bf16 v[38:41], v[134:137], v[186:189], v[38:41]
	v_mfma_f32_16x16x32_bf16 v[34:37], v[142:145], v[186:189], v[34:37]
	v_mfma_f32_16x16x32_bf16 v[22:25], v[134:137], v[182:185], v[22:25]
	v_mfma_f32_16x16x32_bf16 v[18:21], v[142:145], v[182:185], v[18:21]
	v_mfma_f32_16x16x32_bf16 v[6:9], v[134:137], v[178:181], v[6:9]
	v_mfma_f32_16x16x32_bf16 v[2:5], v[142:145], v[178:181], v[2:5]
	s_branch .LBB0_1611
